# conformer conv31 prompt items: tap weights + bias loaded once per workgroup before the item loop (they only depend on the channel block), output stage with v_cvt_pk_bf16_f32 pairs + scalar row bases r
# speedup vs baseline: 1.0249x; 1.0014x over previous
; __device__ __forceinline__ void cf_prompt_items(LAS unsigned char* lds, const bf16_t* PROJ, int it0, int itstride, int nitems, const float* cw, const float* cb, bf16_t* CONVOUT, float* pcfc) {
;     ...
;     for (int it = it0; it < nitems; it += itstride) {
;         const int row0 = (it >> 2) * 32, t0 = row0 % SEQ, b = row0 / SEQ, c0 = (it & 3) * 512;
;         float* state_out = (t0 == SEQ - 32) ? pcfc + (size_t)b * 30 * DM : nullptr;
;         float wv[31];
; #pragma unroll
;         for (int i = 0; i < 31; ++i) wv[i] = cw[i * DM + c0 + tid];
;         const float bias = cb[c0 + tid];
; #pragma unroll
.LBB0_240:
	s_add_u32 s87, s16, 0x4824000
	s_addc_u32 s88, s17, 0
	s_lshl_b32 s1, s0, 11
	s_add_i32 s1, s1, 0
	s_cmp_gt_i32 s0, 31
	s_mov_b32 s39, 0
	s_cselect_b64 s[40:41], -1, 0
	s_sub_i32 s38, s0, 32
	s_lshl_b64 s[42:43], s[38:39], 13
	s_cmp_gt_i32 s0, 23
	s_cselect_b64 s[44:45], -1, 0
	s_sub_i32 s38, s0, 24
	s_lshl_b64 s[46:47], s[38:39], 13
	s_cmp_gt_i32 s0, 15
	s_cselect_b64 s[48:49], -1, 0
	s_add_i32 s38, s0, -16
	s_lshl_b64 s[50:51], s[38:39], 13
	s_cmp_gt_i32 s0, 7
	s_cselect_b64 s[52:53], -1, 0
	s_add_i32 s38, s0, -8
	v_ashrrev_i32_e32 v45, 31, v44
	s_lshl_b64 s[54:55], s[38:39], 13
	v_lshl_add_u64 v[48:49], v[44:45], 1, s[6:7]
	v_lshl_add_u32 v45, v13, 2, s1
	s_cmp_gt_i32 s0, -1
	s_mov_b32 s1, s39
	s_cselect_b64 s[56:57], -1, 0
	s_lshl_b64 s[58:59], s[0:1], 13
	s_cmp_gt_i32 s0, -9
	s_cselect_b64 s[60:61], -1, 0
	s_add_i32 s38, s0, 8
	s_lshl_b64 s[62:63], s[38:39], 13
	s_cmpk_gt_i32 s0, 0xffef
	s_cselect_b64 s[64:65], -1, 0
	s_add_i32 s38, s0, 16
	s_lshl_b64 s[66:67], s[38:39], 13
	s_cmpk_gt_i32 s0, 0xffe7
	v_lshl_add_u32 v52, v44, 2, 0
	s_cselect_b64 s[68:69], -1, 0
	s_add_i32 s38, s0, 24
	v_add_u32_e32 v53, 0x10000, v52
	v_add_u32_e32 v54, 0x10800, v52
	v_add_u32_e32 v55, 0x11000, v52
	v_add_u32_e32 v56, 0x11800, v52
	v_add_u32_e32 v57, 0x12000, v52
	v_add_u32_e32 v58, 0x12800, v52
	v_add_u32_e32 v59, 0x13000, v52
	v_add_u32_e32 v60, 0x13800, v52
	v_add_u32_e32 v61, 0x14000, v52
	v_add_u32_e32 v62, 0x14800, v52
	v_add_u32_e32 v63, 0x15000, v52
	v_add_u32_e32 v64, 0x15800, v52
	v_add_u32_e32 v65, 0x16000, v52
	v_add_u32_e32 v66, 0x16800, v52
	v_add_u32_e32 v67, 0x17000, v52
	v_add_u32_e32 v68, 0x17800, v52
	v_add_u32_e32 v69, 0x18000, v52
	v_add_u32_e32 v70, 0x18800, v52
	v_add_u32_e32 v71, 0x19000, v52
	v_add_u32_e32 v72, 0x19800, v52
	v_add_u32_e32 v73, 0x1a000, v52
	v_add_u32_e32 v74, 0x1a800, v52
	v_add_u32_e32 v75, 0x1b000, v52
	v_add_u32_e32 v76, 0x1b800, v52
	v_add_u32_e32 v77, 0x1c000, v52
	v_add_u32_e32 v78, 0x1c800, v52
	v_add_u32_e32 v79, 0x1d000, v52
	v_add_u32_e32 v80, 0x1d800, v52
	v_add_u32_e32 v81, 0x1e000, v52
	v_add_u32_e32 v82, 0x1e800, v52
	v_add_u32_e32 v83, 0x10000, v45
	v_add_u32_e32 v84, 0x10010, v45
	v_add_u32_e32 v85, 0x14000, v45
	v_add_u32_e32 v86, 0x14010, v45
	v_add_u32_e32 v87, 0x18000, v45
	v_add_u32_e32 v88, 0x18010, v45
	v_add_u32_e32 v89, 0x1c000, v45
	v_add_u32_e32 v90, 0x1c010, v45
	s_lshl_b64 s[70:71], s[38:39], 13
	s_lshl_b32 s89, s94, 9
	v_lshlrev_b32_e32 v50, 2, v13
	v_mov_b32_e32 v51, v12
	s_movk_i32 s90, 0x7fff
	v_readlane_b32 s91, v253, 2
	s_and_b32 s0, s33, 0x600
	v_add_u32_e32 v36, s0, v44
	v_lshlrev_b32_e32 v36, 2, v36
	s_waitcnt lgkmcnt(0)
	s_mov_b32 s0, s8
	s_mov_b32 s1, s9
	global_load_dword v143, v36, s[0:1]
	s_add_u32 s0, s0, 0x2000
	s_addc_u32 s1, s1, 0
	global_load_dword v142, v36, s[0:1]
	s_add_u32 s0, s0, 0x2000
	s_addc_u32 s1, s1, 0
	global_load_dword v141, v36, s[0:1]
	s_add_u32 s0, s0, 0x2000
	s_addc_u32 s1, s1, 0
	global_load_dword v140, v36, s[0:1]
	s_add_u32 s0, s0, 0x2000
	s_addc_u32 s1, s1, 0
	global_load_dword v139, v36, s[0:1]
	s_add_u32 s0, s0, 0x2000
	s_addc_u32 s1, s1, 0
	global_load_dword v138, v36, s[0:1]
	s_add_u32 s0, s0, 0x2000
	s_addc_u32 s1, s1, 0
	global_load_dword v137, v36, s[0:1]
	s_add_u32 s0, s0, 0x2000
	s_addc_u32 s1, s1, 0
	global_load_dword v136, v36, s[0:1]
	s_add_u32 s0, s0, 0x2000
	s_addc_u32 s1, s1, 0
	global_load_dword v127, v36, s[0:1]
	s_add_u32 s0, s0, 0x2000
	s_addc_u32 s1, s1, 0
	global_load_dword v126, v36, s[0:1]
	s_add_u32 s0, s0, 0x2000
	s_addc_u32 s1, s1, 0
	global_load_dword v123, v36, s[0:1]
	s_add_u32 s0, s0, 0x2000
	s_addc_u32 s1, s1, 0
	global_load_dword v120, v36, s[0:1]
	s_add_u32 s0, s0, 0x2000
	s_addc_u32 s1, s1, 0
	global_load_dword v117, v36, s[0:1]
	s_add_u32 s0, s0, 0x2000
	s_addc_u32 s1, s1, 0
	global_load_dword v114, v36, s[0:1]
	s_add_u32 s0, s0, 0x2000
	s_addc_u32 s1, s1, 0
	global_load_dword v111, v36, s[0:1]
	s_add_u32 s0, s0, 0x2000
	s_addc_u32 s1, s1, 0
	global_load_dword v108, v36, s[0:1]
	s_add_u32 s0, s0, 0x2000
	s_addc_u32 s1, s1, 0
	global_load_dword v106, v36, s[0:1]
	s_add_u32 s0, s0, 0x2000
	s_addc_u32 s1, s1, 0
	global_load_dword v105, v36, s[0:1]
	s_add_u32 s0, s0, 0x2000
	s_addc_u32 s1, s1, 0
	global_load_dword v104, v36, s[0:1]
	s_add_u32 s0, s0, 0x2000
	s_addc_u32 s1, s1, 0
	global_load_dword v103, v36, s[0:1]
	s_add_u32 s0, s0, 0x2000
	s_addc_u32 s1, s1, 0
	global_load_dword v102, v36, s[0:1]
	s_add_u32 s0, s0, 0x2000
	s_addc_u32 s1, s1, 0
	global_load_dword v101, v36, s[0:1]
	s_add_u32 s0, s0, 0x2000
	s_addc_u32 s1, s1, 0
	global_load_dword v100, v36, s[0:1]
	s_add_u32 s0, s0, 0x2000
	s_addc_u32 s1, s1, 0
	global_load_dword v99, v36, s[0:1]
	s_add_u32 s0, s0, 0x2000
	s_addc_u32 s1, s1, 0
	global_load_dword v98, v36, s[0:1]
	s_add_u32 s0, s0, 0x2000
	s_addc_u32 s1, s1, 0
	global_load_dword v97, v36, s[0:1]
	s_add_u32 s0, s0, 0x2000
	s_addc_u32 s1, s1, 0
	global_load_dword v96, v36, s[0:1]
	s_add_u32 s0, s0, 0x2000
	s_addc_u32 s1, s1, 0
	global_load_dword v95, v36, s[0:1]
	s_add_u32 s0, s0, 0x2000
	s_addc_u32 s1, s1, 0
	global_load_dword v94, v36, s[0:1]
	s_add_u32 s0, s0, 0x2000
	s_addc_u32 s1, s1, 0
	global_load_dword v93, v36, s[0:1]
	s_add_u32 s0, s0, 0x2000
	s_addc_u32 s1, s1, 0
	global_load_dword v92, v36, s[0:1]
	global_load_dword v91, v36, s[10:11]
	s_branch .LBB0_243

; #define LAS __attribute__((address_space(3)))
;     static __device__ __forceinline__ void run(float (&acc)[32], const float (&w)[31], const LAS float* us) {
;         const float v = us[J * 512];
;         constexpr int TLO = (J - 30 > 0) ? J - 30 : 0, THI = (J < 31) ? J : 31;
; #pragma unroll
;         for (int t = TLO; t <= THI; ++t) acc[t] += v * w[J - t];
;         if constexpr (J + 1 < 62) CfLds<J + 1>::run(acc, w, us);
;     }
; __device__ __forceinline__ void cf_prompt_items(LAS unsigned char* lds, const bf16_t* PROJ, int it0, int itstride, int nitems, const float* cw, const float* cb, bf16_t* CONVOUT, float* pcfc) {
;     ...
;         float acc[32];
; #pragma unroll
;         for (int t = 0; t < 32; ++t) acc[t] = bias;
;         CfLds<0>::run(acc, wv, Us + tid);
.LBB0_242:
	v_add_u32_e32 v160, 0x8000, v52
	ds_read2st64_b32 v[144:145], v52 offset0:0 offset1:8
	ds_read2st64_b32 v[146:147], v52 offset0:8 offset1:16
	ds_read2st64_b32 v[148:149], v52 offset0:16 offset1:24
	ds_read2st64_b32 v[150:151], v52 offset0:24 offset1:32
	ds_read2st64_b32 v[152:153], v52 offset0:32 offset1:40
	ds_read2st64_b32 v[154:155], v52 offset0:40 offset1:48
	s_and_b32 s82, s75, 0xffffffe0
	s_lshl_b32 s38, s83, 1
	s_ashr_i32 s83, s82, 31
	s_lshl_b64 s[0:1], s[82:83], 12
	s_waitcnt vmcnt(0)
	s_andn2_b64 vcc, exec, s[80:81]
	s_mov_b32 s33, s93
	ds_read2st64_b32 v[156:157], v52 offset0:48 offset1:56
	s_waitcnt lgkmcnt(6)
	v_pk_fma_f32 v[176:177], v[144:145], v[142:143], v[90:91] op_sel:[0,1,1] op_sel_hi:[1,1,1]
	ds_read2st64_b32 v[158:159], v52 offset0:56 offset1:64
	s_waitcnt lgkmcnt(6)
	v_pk_fma_f32 v[176:177], v[146:147], v[142:143], v[176:177] op_sel:[0,0,0] op_sel_hi:[1,0,1]
	ds_read2st64_b32 v[144:145], v52 offset0:64 offset1:72
	s_waitcnt lgkmcnt(6)
	v_pk_fma_f32 v[176:177], v[148:149], v[140:141], v[176:177] op_sel:[0,1,0] op_sel_hi:[1,1,1]
	v_pk_fma_f32 v[178:179], v[148:149], v[142:143], v[90:91] op_sel:[0,1,1] op_sel_hi:[1,1,1]
	ds_read2st64_b32 v[146:147], v52 offset0:72 offset1:80
	s_waitcnt lgkmcnt(6)
	v_pk_fma_f32 v[176:177], v[150:151], v[140:141], v[176:177] op_sel:[0,0,0] op_sel_hi:[1,0,1]
	v_pk_fma_f32 v[178:179], v[150:151], v[142:143], v[178:179] op_sel:[0,0,0] op_sel_hi:[1,0,1]
	ds_read2st64_b32 v[148:149], v52 offset0:80 offset1:88
	s_waitcnt lgkmcnt(6)
	v_pk_fma_f32 v[176:177], v[152:153], v[138:139], v[176:177] op_sel:[0,1,0] op_sel_hi:[1,1,1]
	v_pk_fma_f32 v[178:179], v[152:153], v[140:141], v[178:179] op_sel:[0,1,0] op_sel_hi:[1,1,1]
	v_pk_fma_f32 v[180:181], v[152:153], v[142:143], v[90:91] op_sel:[0,1,1] op_sel_hi:[1,1,1]
	ds_read2st64_b32 v[150:151], v52 offset0:88 offset1:96
	s_waitcnt lgkmcnt(6)
	v_pk_fma_f32 v[176:177], v[154:155], v[138:139], v[176:177] op_sel:[0,0,0] op_sel_hi:[1,0,1]
	v_pk_fma_f32 v[178:179], v[154:155], v[140:141], v[178:179] op_sel:[0,0,0] op_sel_hi:[1,0,1]
	v_pk_fma_f32 v[180:181], v[154:155], v[142:143], v[180:181] op_sel:[0,0,0] op_sel_hi:[1,0,1]
	ds_read2st64_b32 v[152:153], v52 offset0:96 offset1:104
	s_waitcnt lgkmcnt(6)
	v_pk_fma_f32 v[176:177], v[156:157], v[136:137], v[176:177] op_sel:[0,1,0] op_sel_hi:[1,1,1]
	v_pk_fma_f32 v[178:179], v[156:157], v[138:139], v[178:179] op_sel:[0,1,0] op_sel_hi:[1,1,1]
	v_pk_fma_f32 v[180:181], v[156:157], v[140:141], v[180:181] op_sel:[0,1,0] op_sel_hi:[1,1,1]
	v_pk_fma_f32 v[182:183], v[156:157], v[142:143], v[90:91] op_sel:[0,1,1] op_sel_hi:[1,1,1]
	ds_read2st64_b32 v[154:155], v52 offset0:104 offset1:112
	s_waitcnt lgkmcnt(6)
	v_pk_fma_f32 v[176:177], v[158:159], v[136:137], v[176:177] op_sel:[0,0,0] op_sel_hi:[1,0,1]
	v_pk_fma_f32 v[178:179], v[158:159], v[138:139], v[178:179] op_sel:[0,0,0] op_sel_hi:[1,0,1]
	v_pk_fma_f32 v[180:181], v[158:159], v[140:141], v[180:181] op_sel:[0,0,0] op_sel_hi:[1,0,1]
	v_pk_fma_f32 v[182:183], v[158:159], v[142:143], v[182:183] op_sel:[0,0,0] op_sel_hi:[1,0,1]
	ds_read2st64_b32 v[156:157], v52 offset0:112 offset1:120
	s_waitcnt lgkmcnt(6)
	v_pk_fma_f32 v[176:177], v[144:145], v[126:127], v[176:177] op_sel:[0,1,0] op_sel_hi:[1,1,1]
	v_pk_fma_f32 v[178:179], v[144:145], v[136:137], v[178:179] op_sel:[0,1,0] op_sel_hi:[1,1,1]
	v_pk_fma_f32 v[180:181], v[144:145], v[138:139], v[180:181] op_sel:[0,1,0] op_sel_hi:[1,1,1]
	v_pk_fma_f32 v[182:183], v[144:145], v[140:141], v[182:183] op_sel:[0,1,0] op_sel_hi:[1,1,1]
	v_pk_fma_f32 v[184:185], v[144:145], v[142:143], v[90:91] op_sel:[0,1,1] op_sel_hi:[1,1,1]
	ds_read2st64_b32 v[158:159], v52 offset0:120 offset1:128
	s_waitcnt lgkmcnt(6)
	v_pk_fma_f32 v[176:177], v[146:147], v[126:127], v[176:177] op_sel:[0,0,0] op_sel_hi:[1,0,1]
	v_pk_fma_f32 v[178:179], v[146:147], v[136:137], v[178:179] op_sel:[0,0,0] op_sel_hi:[1,0,1]
	v_pk_fma_f32 v[180:181], v[146:147], v[138:139], v[180:181] op_sel:[0,0,0] op_sel_hi:[1,0,1]
	v_pk_fma_f32 v[182:183], v[146:147], v[140:141], v[182:183] op_sel:[0,0,0] op_sel_hi:[1,0,1]
	v_pk_fma_f32 v[184:185], v[146:147], v[142:143], v[184:185] op_sel:[0,0,0] op_sel_hi:[1,0,1]
	ds_read2st64_b32 v[144:145], v52 offset0:128 offset1:136
	s_waitcnt lgkmcnt(6)
	v_pk_fma_f32 v[176:177], v[148:149], v[122:123], v[176:177] op_sel:[0,1,0] op_sel_hi:[1,1,1]
	v_pk_fma_f32 v[178:179], v[148:149], v[126:127], v[178:179] op_sel:[0,1,0] op_sel_hi:[1,1,1]
	v_pk_fma_f32 v[180:181], v[148:149], v[136:137], v[180:181] op_sel:[0,1,0] op_sel_hi:[1,1,1]
	v_pk_fma_f32 v[182:183], v[148:149], v[138:139], v[182:183] op_sel:[0,1,0] op_sel_hi:[1,1,1]
	v_pk_fma_f32 v[184:185], v[148:149], v[140:141], v[184:185] op_sel:[0,1,0] op_sel_hi:[1,1,1]
	v_pk_fma_f32 v[186:187], v[148:149], v[142:143], v[90:91] op_sel:[0,1,1] op_sel_hi:[1,1,1]
	ds_read2st64_b32 v[146:147], v52 offset0:136 offset1:144
	s_waitcnt lgkmcnt(6)
	v_pk_fma_f32 v[176:177], v[150:151], v[120:121], v[176:177] op_sel:[0,0,0] op_sel_hi:[1,0,1]
	v_pk_fma_f32 v[178:179], v[150:151], v[126:127], v[178:179] op_sel:[0,0,0] op_sel_hi:[1,0,1]
	v_pk_fma_f32 v[180:181], v[150:151], v[136:137], v[180:181] op_sel:[0,0,0] op_sel_hi:[1,0,1]
	v_pk_fma_f32 v[182:183], v[150:151], v[138:139], v[182:183] op_sel:[0,0,0] op_sel_hi:[1,0,1]
	v_pk_fma_f32 v[184:185], v[150:151], v[140:141], v[184:185] op_sel:[0,0,0] op_sel_hi:[1,0,1]
	v_pk_fma_f32 v[186:187], v[150:151], v[142:143], v[186:187] op_sel:[0,0,0] op_sel_hi:[1,0,1]
	ds_read2st64_b32 v[148:149], v52 offset0:144 offset1:152
	s_waitcnt lgkmcnt(6)
; #define LAS __attribute__((address_space(3)))
;     static __device__ __forceinline__ void run(float (&acc)[32], const float (&w)[31], const LAS float* us) {
;         const float v = us[J * 512];
;         constexpr int TLO = (J - 30 > 0) ? J - 30 : 0, THI = (J < 31) ? J : 31;
; #pragma unroll
;         for (int t = TLO; t <= THI; ++t) acc[t] += v * w[J - t];
;         if constexpr (J + 1 < 62) CfLds<J + 1>::run(acc, w, us);
;     }
; __device__ __forceinline__ void cf_prompt_items(LAS unsigned char* lds, const bf16_t* PROJ, int it0, int itstride, int nitems, const float* cw, const float* cb, bf16_t* CONVOUT, float* pcfc) {
;     ...
;         float acc[32];
; #pragma unroll
;         for (int t = 0; t < 32; ++t) acc[t] = bias;
;         CfLds<0>::run(acc, wv, Us + tid);
	v_pk_fma_f32 v[176:177], v[152:153], v[116:117], v[176:177] op_sel:[0,1,0] op_sel_hi:[1,1,1]
	v_pk_fma_f32 v[178:179], v[152:153], v[122:123], v[178:179] op_sel:[0,1,0] op_sel_hi:[1,1,1]
	v_pk_fma_f32 v[180:181], v[152:153], v[126:127], v[180:181] op_sel:[0,1,0] op_sel_hi:[1,1,1]
	v_pk_fma_f32 v[182:183], v[152:153], v[136:137], v[182:183] op_sel:[0,1,0] op_sel_hi:[1,1,1]
	v_pk_fma_f32 v[184:185], v[152:153], v[138:139], v[184:185] op_sel:[0,1,0] op_sel_hi:[1,1,1]
	v_pk_fma_f32 v[186:187], v[152:153], v[140:141], v[186:187] op_sel:[0,1,0] op_sel_hi:[1,1,1]
	v_pk_fma_f32 v[188:189], v[152:153], v[142:143], v[90:91] op_sel:[0,1,1] op_sel_hi:[1,1,1]
	ds_read2st64_b32 v[150:151], v52 offset0:152 offset1:160
	s_waitcnt lgkmcnt(6)
	v_pk_fma_f32 v[176:177], v[154:155], v[114:115], v[176:177] op_sel:[0,0,0] op_sel_hi:[1,0,1]
	v_pk_fma_f32 v[178:179], v[154:155], v[120:121], v[178:179] op_sel:[0,0,0] op_sel_hi:[1,0,1]
	v_pk_fma_f32 v[180:181], v[154:155], v[126:127], v[180:181] op_sel:[0,0,0] op_sel_hi:[1,0,1]
	v_pk_fma_f32 v[182:183], v[154:155], v[136:137], v[182:183] op_sel:[0,0,0] op_sel_hi:[1,0,1]
	v_pk_fma_f32 v[184:185], v[154:155], v[138:139], v[184:185] op_sel:[0,0,0] op_sel_hi:[1,0,1]
	v_pk_fma_f32 v[186:187], v[154:155], v[140:141], v[186:187] op_sel:[0,0,0] op_sel_hi:[1,0,1]
	v_pk_fma_f32 v[188:189], v[154:155], v[142:143], v[188:189] op_sel:[0,0,0] op_sel_hi:[1,0,1]
	ds_read2st64_b32 v[152:153], v52 offset0:160 offset1:168
	s_waitcnt lgkmcnt(6)
	v_pk_fma_f32 v[176:177], v[156:157], v[110:111], v[176:177] op_sel:[0,1,0] op_sel_hi:[1,1,1]
	v_pk_fma_f32 v[178:179], v[156:157], v[116:117], v[178:179] op_sel:[0,1,0] op_sel_hi:[1,1,1]
	v_pk_fma_f32 v[180:181], v[156:157], v[122:123], v[180:181] op_sel:[0,1,0] op_sel_hi:[1,1,1]
	v_pk_fma_f32 v[182:183], v[156:157], v[126:127], v[182:183] op_sel:[0,1,0] op_sel_hi:[1,1,1]
	v_pk_fma_f32 v[184:185], v[156:157], v[136:137], v[184:185] op_sel:[0,1,0] op_sel_hi:[1,1,1]
	v_pk_fma_f32 v[186:187], v[156:157], v[138:139], v[186:187] op_sel:[0,1,0] op_sel_hi:[1,1,1]
	v_pk_fma_f32 v[188:189], v[156:157], v[140:141], v[188:189] op_sel:[0,1,0] op_sel_hi:[1,1,1]
	v_pk_fma_f32 v[190:191], v[156:157], v[142:143], v[90:91] op_sel:[0,1,1] op_sel_hi:[1,1,1]
	ds_read2st64_b32 v[154:155], v52 offset0:168 offset1:176
	s_waitcnt lgkmcnt(6)
	v_pk_fma_f32 v[176:177], v[158:159], v[108:109], v[176:177] op_sel:[0,0,0] op_sel_hi:[1,0,1]
	v_pk_fma_f32 v[178:179], v[158:159], v[114:115], v[178:179] op_sel:[0,0,0] op_sel_hi:[1,0,1]
	v_pk_fma_f32 v[180:181], v[158:159], v[120:121], v[180:181] op_sel:[0,0,0] op_sel_hi:[1,0,1]
	v_pk_fma_f32 v[182:183], v[158:159], v[126:127], v[182:183] op_sel:[0,0,0] op_sel_hi:[1,0,1]
	v_pk_fma_f32 v[184:185], v[158:159], v[136:137], v[184:185] op_sel:[0,0,0] op_sel_hi:[1,0,1]
	v_pk_fma_f32 v[186:187], v[158:159], v[138:139], v[186:187] op_sel:[0,0,0] op_sel_hi:[1,0,1]
	v_pk_fma_f32 v[188:189], v[158:159], v[140:141], v[188:189] op_sel:[0,0,0] op_sel_hi:[1,0,1]
	v_pk_fma_f32 v[190:191], v[158:159], v[142:143], v[190:191] op_sel:[0,0,0] op_sel_hi:[1,0,1]
	ds_read2st64_b32 v[156:157], v52 offset0:176 offset1:184
	s_waitcnt lgkmcnt(6)
	v_pk_fma_f32 v[176:177], v[144:145], v[106:107], v[176:177] op_sel:[0,0,0] op_sel_hi:[1,0,1]
	v_pk_fma_f32 v[178:179], v[144:145], v[110:111], v[178:179] op_sel:[0,1,0] op_sel_hi:[1,1,1]
	v_pk_fma_f32 v[180:181], v[144:145], v[116:117], v[180:181] op_sel:[0,1,0] op_sel_hi:[1,1,1]
	v_pk_fma_f32 v[182:183], v[144:145], v[122:123], v[182:183] op_sel:[0,1,0] op_sel_hi:[1,1,1]
	v_pk_fma_f32 v[184:185], v[144:145], v[126:127], v[184:185] op_sel:[0,1,0] op_sel_hi:[1,1,1]
	v_pk_fma_f32 v[186:187], v[144:145], v[136:137], v[186:187] op_sel:[0,1,0] op_sel_hi:[1,1,1]
	v_pk_fma_f32 v[188:189], v[144:145], v[138:139], v[188:189] op_sel:[0,1,0] op_sel_hi:[1,1,1]
	v_pk_fma_f32 v[190:191], v[144:145], v[140:141], v[190:191] op_sel:[0,1,0] op_sel_hi:[1,1,1]
	v_pk_fma_f32 v[192:193], v[144:145], v[142:143], v[90:91] op_sel:[0,1,1] op_sel_hi:[1,1,1]
	ds_read2st64_b32 v[158:159], v52 offset0:184 offset1:192
	s_waitcnt lgkmcnt(6)
	v_pk_fma_f32 v[176:177], v[146:147], v[104:105], v[176:177] op_sel:[0,1,0] op_sel_hi:[1,1,1]
	v_pk_fma_f32 v[178:179], v[146:147], v[108:109], v[178:179] op_sel:[0,0,0] op_sel_hi:[1,0,1]
	v_pk_fma_f32 v[180:181], v[146:147], v[114:115], v[180:181] op_sel:[0,0,0] op_sel_hi:[1,0,1]
	v_pk_fma_f32 v[182:183], v[146:147], v[120:121], v[182:183] op_sel:[0,0,0] op_sel_hi:[1,0,1]
	v_pk_fma_f32 v[184:185], v[146:147], v[126:127], v[184:185] op_sel:[0,0,0] op_sel_hi:[1,0,1]
	v_pk_fma_f32 v[186:187], v[146:147], v[136:137], v[186:187] op_sel:[0,0,0] op_sel_hi:[1,0,1]
	v_pk_fma_f32 v[188:189], v[146:147], v[138:139], v[188:189] op_sel:[0,0,0] op_sel_hi:[1,0,1]
	v_pk_fma_f32 v[190:191], v[146:147], v[140:141], v[190:191] op_sel:[0,0,0] op_sel_hi:[1,0,1]
	v_pk_fma_f32 v[192:193], v[146:147], v[142:143], v[192:193] op_sel:[0,0,0] op_sel_hi:[1,0,1]
	ds_read2st64_b32 v[144:145], v52 offset0:192 offset1:200
	s_waitcnt lgkmcnt(6)
	v_pk_fma_f32 v[176:177], v[148:149], v[104:105], v[176:177] op_sel:[0,0,0] op_sel_hi:[1,0,1]
	v_pk_fma_f32 v[178:179], v[148:149], v[106:107], v[178:179] op_sel:[0,0,0] op_sel_hi:[1,0,1]
	v_pk_fma_f32 v[180:181], v[148:149], v[110:111], v[180:181] op_sel:[0,1,0] op_sel_hi:[1,1,1]
	v_pk_fma_f32 v[182:183], v[148:149], v[116:117], v[182:183] op_sel:[0,1,0] op_sel_hi:[1,1,1]
	v_pk_fma_f32 v[184:185], v[148:149], v[122:123], v[184:185] op_sel:[0,1,0] op_sel_hi:[1,1,1]
	v_pk_fma_f32 v[186:187], v[148:149], v[126:127], v[186:187] op_sel:[0,1,0] op_sel_hi:[1,1,1]
	v_pk_fma_f32 v[188:189], v[148:149], v[136:137], v[188:189] op_sel:[0,1,0] op_sel_hi:[1,1,1]
	v_pk_fma_f32 v[190:191], v[148:149], v[138:139], v[190:191] op_sel:[0,1,0] op_sel_hi:[1,1,1]
	v_pk_fma_f32 v[192:193], v[148:149], v[140:141], v[192:193] op_sel:[0,1,0] op_sel_hi:[1,1,1]
	v_pk_fma_f32 v[194:195], v[148:149], v[142:143], v[90:91] op_sel:[0,1,1] op_sel_hi:[1,1,1]
	ds_read2st64_b32 v[146:147], v52 offset0:200 offset1:208
	s_waitcnt lgkmcnt(6)
; #define LAS __attribute__((address_space(3)))
;     static __device__ __forceinline__ void run(float (&acc)[32], const float (&w)[31], const LAS float* us) {
;         const float v = us[J * 512];
;         constexpr int TLO = (J - 30 > 0) ? J - 30 : 0, THI = (J < 31) ? J : 31;
; #pragma unroll
;         for (int t = TLO; t <= THI; ++t) acc[t] += v * w[J - t];
;         if constexpr (J + 1 < 62) CfLds<J + 1>::run(acc, w, us);
;     }
; __device__ __forceinline__ void cf_prompt_items(LAS unsigned char* lds, const bf16_t* PROJ, int it0, int itstride, int nitems, const float* cw, const float* cb, bf16_t* CONVOUT, float* pcfc) {
;     ...
;         float acc[32];
; #pragma unroll
;         for (int t = 0; t < 32; ++t) acc[t] = bias;
;         CfLds<0>::run(acc, wv, Us + tid);
	v_pk_fma_f32 v[176:177], v[150:151], v[102:103], v[176:177] op_sel:[0,1,0] op_sel_hi:[1,1,1]
	v_pk_fma_f32 v[178:179], v[150:151], v[104:105], v[178:179] op_sel:[0,1,0] op_sel_hi:[1,1,1]
	v_pk_fma_f32 v[180:181], v[150:151], v[108:109], v[180:181] op_sel:[0,0,0] op_sel_hi:[1,0,1]
	v_pk_fma_f32 v[182:183], v[150:151], v[114:115], v[182:183] op_sel:[0,0,0] op_sel_hi:[1,0,1]
	v_pk_fma_f32 v[184:185], v[150:151], v[120:121], v[184:185] op_sel:[0,0,0] op_sel_hi:[1,0,1]
	v_pk_fma_f32 v[186:187], v[150:151], v[126:127], v[186:187] op_sel:[0,0,0] op_sel_hi:[1,0,1]
	v_pk_fma_f32 v[188:189], v[150:151], v[136:137], v[188:189] op_sel:[0,0,0] op_sel_hi:[1,0,1]
	v_pk_fma_f32 v[190:191], v[150:151], v[138:139], v[190:191] op_sel:[0,0,0] op_sel_hi:[1,0,1]
	v_pk_fma_f32 v[192:193], v[150:151], v[140:141], v[192:193] op_sel:[0,0,0] op_sel_hi:[1,0,1]
	v_pk_fma_f32 v[194:195], v[150:151], v[142:143], v[194:195] op_sel:[0,0,0] op_sel_hi:[1,0,1]
	ds_read2st64_b32 v[148:149], v52 offset0:208 offset1:216
	s_waitcnt lgkmcnt(6)
	v_pk_fma_f32 v[176:177], v[152:153], v[102:103], v[176:177] op_sel:[0,0,0] op_sel_hi:[1,0,1]
	v_pk_fma_f32 v[178:179], v[152:153], v[104:105], v[178:179] op_sel:[0,0,0] op_sel_hi:[1,0,1]
	v_pk_fma_f32 v[180:181], v[152:153], v[106:107], v[180:181] op_sel:[0,0,0] op_sel_hi:[1,0,1]
	v_pk_fma_f32 v[182:183], v[152:153], v[110:111], v[182:183] op_sel:[0,1,0] op_sel_hi:[1,1,1]
	v_pk_fma_f32 v[184:185], v[152:153], v[116:117], v[184:185] op_sel:[0,1,0] op_sel_hi:[1,1,1]
	v_pk_fma_f32 v[186:187], v[152:153], v[122:123], v[186:187] op_sel:[0,1,0] op_sel_hi:[1,1,1]
	v_pk_fma_f32 v[188:189], v[152:153], v[126:127], v[188:189] op_sel:[0,1,0] op_sel_hi:[1,1,1]
	v_pk_fma_f32 v[190:191], v[152:153], v[136:137], v[190:191] op_sel:[0,1,0] op_sel_hi:[1,1,1]
	v_pk_fma_f32 v[192:193], v[152:153], v[138:139], v[192:193] op_sel:[0,1,0] op_sel_hi:[1,1,1]
	v_pk_fma_f32 v[194:195], v[152:153], v[140:141], v[194:195] op_sel:[0,1,0] op_sel_hi:[1,1,1]
	v_pk_fma_f32 v[196:197], v[152:153], v[142:143], v[90:91] op_sel:[0,1,1] op_sel_hi:[1,1,1]
	ds_read2st64_b32 v[150:151], v52 offset0:216 offset1:224
	s_waitcnt lgkmcnt(6)
	v_pk_fma_f32 v[176:177], v[154:155], v[100:101], v[176:177] op_sel:[0,1,0] op_sel_hi:[1,1,1]
	v_pk_fma_f32 v[178:179], v[154:155], v[102:103], v[178:179] op_sel:[0,1,0] op_sel_hi:[1,1,1]
	v_pk_fma_f32 v[180:181], v[154:155], v[104:105], v[180:181] op_sel:[0,1,0] op_sel_hi:[1,1,1]
	v_pk_fma_f32 v[182:183], v[154:155], v[108:109], v[182:183] op_sel:[0,0,0] op_sel_hi:[1,0,1]
	v_pk_fma_f32 v[184:185], v[154:155], v[114:115], v[184:185] op_sel:[0,0,0] op_sel_hi:[1,0,1]
	v_pk_fma_f32 v[186:187], v[154:155], v[120:121], v[186:187] op_sel:[0,0,0] op_sel_hi:[1,0,1]
	v_pk_fma_f32 v[188:189], v[154:155], v[126:127], v[188:189] op_sel:[0,0,0] op_sel_hi:[1,0,1]
	v_pk_fma_f32 v[190:191], v[154:155], v[136:137], v[190:191] op_sel:[0,0,0] op_sel_hi:[1,0,1]
	v_pk_fma_f32 v[192:193], v[154:155], v[138:139], v[192:193] op_sel:[0,0,0] op_sel_hi:[1,0,1]
	v_pk_fma_f32 v[194:195], v[154:155], v[140:141], v[194:195] op_sel:[0,0,0] op_sel_hi:[1,0,1]
	v_pk_fma_f32 v[196:197], v[154:155], v[142:143], v[196:197] op_sel:[0,0,0] op_sel_hi:[1,0,1]
	ds_read2st64_b32 v[152:153], v52 offset0:224 offset1:232
	s_waitcnt lgkmcnt(6)
	v_pk_fma_f32 v[176:177], v[156:157], v[100:101], v[176:177] op_sel:[0,0,0] op_sel_hi:[1,0,1]
	v_pk_fma_f32 v[178:179], v[156:157], v[102:103], v[178:179] op_sel:[0,0,0] op_sel_hi:[1,0,1]
	v_pk_fma_f32 v[180:181], v[156:157], v[104:105], v[180:181] op_sel:[0,0,0] op_sel_hi:[1,0,1]
	v_pk_fma_f32 v[182:183], v[156:157], v[106:107], v[182:183] op_sel:[0,0,0] op_sel_hi:[1,0,1]
	v_pk_fma_f32 v[184:185], v[156:157], v[110:111], v[184:185] op_sel:[0,1,0] op_sel_hi:[1,1,1]
	v_pk_fma_f32 v[186:187], v[156:157], v[116:117], v[186:187] op_sel:[0,1,0] op_sel_hi:[1,1,1]
	v_pk_fma_f32 v[188:189], v[156:157], v[122:123], v[188:189] op_sel:[0,1,0] op_sel_hi:[1,1,1]
	v_pk_fma_f32 v[190:191], v[156:157], v[126:127], v[190:191] op_sel:[0,1,0] op_sel_hi:[1,1,1]
	v_pk_fma_f32 v[192:193], v[156:157], v[136:137], v[192:193] op_sel:[0,1,0] op_sel_hi:[1,1,1]
	v_pk_fma_f32 v[194:195], v[156:157], v[138:139], v[194:195] op_sel:[0,1,0] op_sel_hi:[1,1,1]
	v_pk_fma_f32 v[196:197], v[156:157], v[140:141], v[196:197] op_sel:[0,1,0] op_sel_hi:[1,1,1]
	v_pk_fma_f32 v[198:199], v[156:157], v[142:143], v[90:91] op_sel:[0,1,1] op_sel_hi:[1,1,1]
	ds_read2st64_b32 v[154:155], v52 offset0:232 offset1:240
	s_waitcnt lgkmcnt(6)
	v_pk_fma_f32 v[176:177], v[158:159], v[98:99], v[176:177] op_sel:[0,1,0] op_sel_hi:[1,1,1]
	v_pk_fma_f32 v[178:179], v[158:159], v[100:101], v[178:179] op_sel:[0,1,0] op_sel_hi:[1,1,1]
	v_pk_fma_f32 v[180:181], v[158:159], v[102:103], v[180:181] op_sel:[0,1,0] op_sel_hi:[1,1,1]
	v_pk_fma_f32 v[182:183], v[158:159], v[104:105], v[182:183] op_sel:[0,1,0] op_sel_hi:[1,1,1]
	v_pk_fma_f32 v[184:185], v[158:159], v[108:109], v[184:185] op_sel:[0,0,0] op_sel_hi:[1,0,1]
	v_pk_fma_f32 v[186:187], v[158:159], v[114:115], v[186:187] op_sel:[0,0,0] op_sel_hi:[1,0,1]
	v_pk_fma_f32 v[188:189], v[158:159], v[120:121], v[188:189] op_sel:[0,0,0] op_sel_hi:[1,0,1]
	v_pk_fma_f32 v[190:191], v[158:159], v[126:127], v[190:191] op_sel:[0,0,0] op_sel_hi:[1,0,1]
	v_pk_fma_f32 v[192:193], v[158:159], v[136:137], v[192:193] op_sel:[0,0,0] op_sel_hi:[1,0,1]
	v_pk_fma_f32 v[194:195], v[158:159], v[138:139], v[194:195] op_sel:[0,0,0] op_sel_hi:[1,0,1]
	v_pk_fma_f32 v[196:197], v[158:159], v[140:141], v[196:197] op_sel:[0,0,0] op_sel_hi:[1,0,1]
	v_pk_fma_f32 v[198:199], v[158:159], v[142:143], v[198:199] op_sel:[0,0,0] op_sel_hi:[1,0,1]
	ds_read2st64_b32 v[156:157], v52 offset0:240 offset1:248
	s_waitcnt lgkmcnt(6)
; #define LAS __attribute__((address_space(3)))
;     static __device__ __forceinline__ void run(float (&acc)[32], const float (&w)[31], const LAS float* us) {
;         const float v = us[J * 512];
;         constexpr int TLO = (J - 30 > 0) ? J - 30 : 0, THI = (J < 31) ? J : 31;
; #pragma unroll
;         for (int t = TLO; t <= THI; ++t) acc[t] += v * w[J - t];
;         if constexpr (J + 1 < 62) CfLds<J + 1>::run(acc, w, us);
;     }
; __device__ __forceinline__ void cf_prompt_items(LAS unsigned char* lds, const bf16_t* PROJ, int it0, int itstride, int nitems, const float* cw, const float* cb, bf16_t* CONVOUT, float* pcfc) {
;     ...
;         float acc[32];
; #pragma unroll
;         for (int t = 0; t < 32; ++t) acc[t] = bias;
;         CfLds<0>::run(acc, wv, Us + tid);
	v_pk_fma_f32 v[176:177], v[144:145], v[98:99], v[176:177] op_sel:[0,0,0] op_sel_hi:[1,0,1]
	v_pk_fma_f32 v[178:179], v[144:145], v[100:101], v[178:179] op_sel:[0,0,0] op_sel_hi:[1,0,1]
	v_pk_fma_f32 v[180:181], v[144:145], v[102:103], v[180:181] op_sel:[0,0,0] op_sel_hi:[1,0,1]
	v_pk_fma_f32 v[182:183], v[144:145], v[104:105], v[182:183] op_sel:[0,0,0] op_sel_hi:[1,0,1]
	v_pk_fma_f32 v[184:185], v[144:145], v[106:107], v[184:185] op_sel:[0,0,0] op_sel_hi:[1,0,1]
	v_pk_fma_f32 v[186:187], v[144:145], v[110:111], v[186:187] op_sel:[0,1,0] op_sel_hi:[1,1,1]
	v_pk_fma_f32 v[188:189], v[144:145], v[116:117], v[188:189] op_sel:[0,1,0] op_sel_hi:[1,1,1]
	v_pk_fma_f32 v[190:191], v[144:145], v[122:123], v[190:191] op_sel:[0,1,0] op_sel_hi:[1,1,1]
	v_pk_fma_f32 v[192:193], v[144:145], v[126:127], v[192:193] op_sel:[0,1,0] op_sel_hi:[1,1,1]
	v_pk_fma_f32 v[194:195], v[144:145], v[136:137], v[194:195] op_sel:[0,1,0] op_sel_hi:[1,1,1]
	v_pk_fma_f32 v[196:197], v[144:145], v[138:139], v[196:197] op_sel:[0,1,0] op_sel_hi:[1,1,1]
	v_pk_fma_f32 v[198:199], v[144:145], v[140:141], v[198:199] op_sel:[0,1,0] op_sel_hi:[1,1,1]
	v_pk_fma_f32 v[200:201], v[144:145], v[142:143], v[90:91] op_sel:[0,1,1] op_sel_hi:[1,1,1]
	ds_read2st64_b32 v[158:159], v160 offset0:120 offset1:128
	s_waitcnt lgkmcnt(6)
	v_pk_fma_f32 v[176:177], v[146:147], v[96:97], v[176:177] op_sel:[0,1,0] op_sel_hi:[1,1,1]
	v_pk_fma_f32 v[178:179], v[146:147], v[98:99], v[178:179] op_sel:[0,1,0] op_sel_hi:[1,1,1]
	v_pk_fma_f32 v[180:181], v[146:147], v[100:101], v[180:181] op_sel:[0,1,0] op_sel_hi:[1,1,1]
	v_pk_fma_f32 v[182:183], v[146:147], v[102:103], v[182:183] op_sel:[0,1,0] op_sel_hi:[1,1,1]
	v_pk_fma_f32 v[184:185], v[146:147], v[104:105], v[184:185] op_sel:[0,1,0] op_sel_hi:[1,1,1]
	v_pk_fma_f32 v[186:187], v[146:147], v[108:109], v[186:187] op_sel:[0,0,0] op_sel_hi:[1,0,1]
	v_pk_fma_f32 v[188:189], v[146:147], v[114:115], v[188:189] op_sel:[0,0,0] op_sel_hi:[1,0,1]
	v_pk_fma_f32 v[190:191], v[146:147], v[120:121], v[190:191] op_sel:[0,0,0] op_sel_hi:[1,0,1]
	v_pk_fma_f32 v[192:193], v[146:147], v[126:127], v[192:193] op_sel:[0,0,0] op_sel_hi:[1,0,1]
	v_pk_fma_f32 v[194:195], v[146:147], v[136:137], v[194:195] op_sel:[0,0,0] op_sel_hi:[1,0,1]
	v_pk_fma_f32 v[196:197], v[146:147], v[138:139], v[196:197] op_sel:[0,0,0] op_sel_hi:[1,0,1]
	v_pk_fma_f32 v[198:199], v[146:147], v[140:141], v[198:199] op_sel:[0,0,0] op_sel_hi:[1,0,1]
	v_pk_fma_f32 v[200:201], v[146:147], v[142:143], v[200:201] op_sel:[0,0,0] op_sel_hi:[1,0,1]
	ds_read2st64_b32 v[144:145], v53 offset0:0 offset1:8
	s_waitcnt lgkmcnt(6)
	v_pk_fma_f32 v[176:177], v[148:149], v[96:97], v[176:177] op_sel:[0,0,0] op_sel_hi:[1,0,1]
	v_pk_fma_f32 v[178:179], v[148:149], v[98:99], v[178:179] op_sel:[0,0,0] op_sel_hi:[1,0,1]
	v_pk_fma_f32 v[180:181], v[148:149], v[100:101], v[180:181] op_sel:[0,0,0] op_sel_hi:[1,0,1]
	v_pk_fma_f32 v[182:183], v[148:149], v[102:103], v[182:183] op_sel:[0,0,0] op_sel_hi:[1,0,1]
	v_pk_fma_f32 v[184:185], v[148:149], v[104:105], v[184:185] op_sel:[0,0,0] op_sel_hi:[1,0,1]
	v_pk_fma_f32 v[186:187], v[148:149], v[106:107], v[186:187] op_sel:[0,0,0] op_sel_hi:[1,0,1]
	v_pk_fma_f32 v[188:189], v[148:149], v[110:111], v[188:189] op_sel:[0,1,0] op_sel_hi:[1,1,1]
	v_pk_fma_f32 v[190:191], v[148:149], v[116:117], v[190:191] op_sel:[0,1,0] op_sel_hi:[1,1,1]
	v_pk_fma_f32 v[192:193], v[148:149], v[122:123], v[192:193] op_sel:[0,1,0] op_sel_hi:[1,1,1]
	v_pk_fma_f32 v[194:195], v[148:149], v[126:127], v[194:195] op_sel:[0,1,0] op_sel_hi:[1,1,1]
	v_pk_fma_f32 v[196:197], v[148:149], v[136:137], v[196:197] op_sel:[0,1,0] op_sel_hi:[1,1,1]
	v_pk_fma_f32 v[198:199], v[148:149], v[138:139], v[198:199] op_sel:[0,1,0] op_sel_hi:[1,1,1]
	v_pk_fma_f32 v[200:201], v[148:149], v[140:141], v[200:201] op_sel:[0,1,0] op_sel_hi:[1,1,1]
	v_pk_fma_f32 v[202:203], v[148:149], v[142:143], v[90:91] op_sel:[0,1,1] op_sel_hi:[1,1,1]
	ds_read2st64_b32 v[146:147], v53 offset0:8 offset1:16
	s_waitcnt lgkmcnt(6)
	v_pk_fma_f32 v[176:177], v[150:151], v[94:95], v[176:177] op_sel:[0,1,0] op_sel_hi:[1,1,1]
	v_pk_fma_f32 v[178:179], v[150:151], v[96:97], v[178:179] op_sel:[0,1,0] op_sel_hi:[1,1,1]
	v_pk_fma_f32 v[180:181], v[150:151], v[98:99], v[180:181] op_sel:[0,1,0] op_sel_hi:[1,1,1]
	v_pk_fma_f32 v[182:183], v[150:151], v[100:101], v[182:183] op_sel:[0,1,0] op_sel_hi:[1,1,1]
	v_pk_fma_f32 v[184:185], v[150:151], v[102:103], v[184:185] op_sel:[0,1,0] op_sel_hi:[1,1,1]
	v_pk_fma_f32 v[186:187], v[150:151], v[104:105], v[186:187] op_sel:[0,1,0] op_sel_hi:[1,1,1]
	v_pk_fma_f32 v[188:189], v[150:151], v[108:109], v[188:189] op_sel:[0,0,0] op_sel_hi:[1,0,1]
	v_pk_fma_f32 v[190:191], v[150:151], v[114:115], v[190:191] op_sel:[0,0,0] op_sel_hi:[1,0,1]
	v_pk_fma_f32 v[192:193], v[150:151], v[120:121], v[192:193] op_sel:[0,0,0] op_sel_hi:[1,0,1]
	v_pk_fma_f32 v[194:195], v[150:151], v[126:127], v[194:195] op_sel:[0,0,0] op_sel_hi:[1,0,1]
	v_pk_fma_f32 v[196:197], v[150:151], v[136:137], v[196:197] op_sel:[0,0,0] op_sel_hi:[1,0,1]
	v_pk_fma_f32 v[198:199], v[150:151], v[138:139], v[198:199] op_sel:[0,0,0] op_sel_hi:[1,0,1]
	v_pk_fma_f32 v[200:201], v[150:151], v[140:141], v[200:201] op_sel:[0,0,0] op_sel_hi:[1,0,1]
	v_pk_fma_f32 v[202:203], v[150:151], v[142:143], v[202:203] op_sel:[0,0,0] op_sel_hi:[1,0,1]
	ds_read2st64_b32 v[148:149], v53 offset0:16 offset1:24
	s_waitcnt lgkmcnt(6)
; #define LAS __attribute__((address_space(3)))
;     static __device__ __forceinline__ void run(float (&acc)[32], const float (&w)[31], const LAS float* us) {
;         const float v = us[J * 512];
;         constexpr int TLO = (J - 30 > 0) ? J - 30 : 0, THI = (J < 31) ? J : 31;
; #pragma unroll
;         for (int t = TLO; t <= THI; ++t) acc[t] += v * w[J - t];
;         if constexpr (J + 1 < 62) CfLds<J + 1>::run(acc, w, us);
;     }
; __device__ __forceinline__ void cf_prompt_items(LAS unsigned char* lds, const bf16_t* PROJ, int it0, int itstride, int nitems, const float* cw, const float* cb, bf16_t* CONVOUT, float* pcfc) {
;     ...
;         float acc[32];
; #pragma unroll
;         for (int t = 0; t < 32; ++t) acc[t] = bias;
;         CfLds<0>::run(acc, wv, Us + tid);
	v_pk_fma_f32 v[176:177], v[152:153], v[94:95], v[176:177] op_sel:[0,0,0] op_sel_hi:[1,0,1]
	v_pk_fma_f32 v[178:179], v[152:153], v[96:97], v[178:179] op_sel:[0,0,0] op_sel_hi:[1,0,1]
	v_pk_fma_f32 v[180:181], v[152:153], v[98:99], v[180:181] op_sel:[0,0,0] op_sel_hi:[1,0,1]
	v_pk_fma_f32 v[182:183], v[152:153], v[100:101], v[182:183] op_sel:[0,0,0] op_sel_hi:[1,0,1]
	v_pk_fma_f32 v[184:185], v[152:153], v[102:103], v[184:185] op_sel:[0,0,0] op_sel_hi:[1,0,1]
	v_pk_fma_f32 v[186:187], v[152:153], v[104:105], v[186:187] op_sel:[0,0,0] op_sel_hi:[1,0,1]
	v_pk_fma_f32 v[188:189], v[152:153], v[106:107], v[188:189] op_sel:[0,0,0] op_sel_hi:[1,0,1]
	v_pk_fma_f32 v[190:191], v[152:153], v[110:111], v[190:191] op_sel:[0,1,0] op_sel_hi:[1,1,1]
	v_pk_fma_f32 v[192:193], v[152:153], v[116:117], v[192:193] op_sel:[0,1,0] op_sel_hi:[1,1,1]
	v_pk_fma_f32 v[194:195], v[152:153], v[122:123], v[194:195] op_sel:[0,1,0] op_sel_hi:[1,1,1]
	v_pk_fma_f32 v[196:197], v[152:153], v[126:127], v[196:197] op_sel:[0,1,0] op_sel_hi:[1,1,1]
	v_pk_fma_f32 v[198:199], v[152:153], v[136:137], v[198:199] op_sel:[0,1,0] op_sel_hi:[1,1,1]
	v_pk_fma_f32 v[200:201], v[152:153], v[138:139], v[200:201] op_sel:[0,1,0] op_sel_hi:[1,1,1]
	v_pk_fma_f32 v[202:203], v[152:153], v[140:141], v[202:203] op_sel:[0,1,0] op_sel_hi:[1,1,1]
	v_pk_fma_f32 v[204:205], v[152:153], v[142:143], v[90:91] op_sel:[0,1,1] op_sel_hi:[1,1,1]
	ds_read2st64_b32 v[150:151], v53 offset0:24 offset1:32
	s_waitcnt lgkmcnt(6)
	v_pk_fma_f32 v[176:177], v[154:155], v[92:93], v[176:177] op_sel:[0,1,0] op_sel_hi:[1,1,1]
	v_pk_fma_f32 v[178:179], v[154:155], v[94:95], v[178:179] op_sel:[0,1,0] op_sel_hi:[1,1,1]
	v_pk_fma_f32 v[180:181], v[154:155], v[96:97], v[180:181] op_sel:[0,1,0] op_sel_hi:[1,1,1]
	v_pk_fma_f32 v[182:183], v[154:155], v[98:99], v[182:183] op_sel:[0,1,0] op_sel_hi:[1,1,1]
	v_pk_fma_f32 v[184:185], v[154:155], v[100:101], v[184:185] op_sel:[0,1,0] op_sel_hi:[1,1,1]
	v_pk_fma_f32 v[186:187], v[154:155], v[102:103], v[186:187] op_sel:[0,1,0] op_sel_hi:[1,1,1]
	v_pk_fma_f32 v[188:189], v[154:155], v[104:105], v[188:189] op_sel:[0,1,0] op_sel_hi:[1,1,1]
	v_pk_fma_f32 v[190:191], v[154:155], v[108:109], v[190:191] op_sel:[0,0,0] op_sel_hi:[1,0,1]
	v_pk_fma_f32 v[192:193], v[154:155], v[114:115], v[192:193] op_sel:[0,0,0] op_sel_hi:[1,0,1]
	v_pk_fma_f32 v[194:195], v[154:155], v[120:121], v[194:195] op_sel:[0,0,0] op_sel_hi:[1,0,1]
	v_pk_fma_f32 v[196:197], v[154:155], v[126:127], v[196:197] op_sel:[0,0,0] op_sel_hi:[1,0,1]
	v_pk_fma_f32 v[198:199], v[154:155], v[136:137], v[198:199] op_sel:[0,0,0] op_sel_hi:[1,0,1]
	v_pk_fma_f32 v[200:201], v[154:155], v[138:139], v[200:201] op_sel:[0,0,0] op_sel_hi:[1,0,1]
	v_pk_fma_f32 v[202:203], v[154:155], v[140:141], v[202:203] op_sel:[0,0,0] op_sel_hi:[1,0,1]
	v_pk_fma_f32 v[204:205], v[154:155], v[142:143], v[204:205] op_sel:[0,0,0] op_sel_hi:[1,0,1]
	ds_read2st64_b32 v[152:153], v53 offset0:32 offset1:40
	s_waitcnt lgkmcnt(6)
	v_pk_fma_f32 v[176:177], v[156:157], v[92:93], v[176:177] op_sel:[0,0,0] op_sel_hi:[1,0,1]
	v_pk_fma_f32 v[178:179], v[156:157], v[94:95], v[178:179] op_sel:[0,0,0] op_sel_hi:[1,0,1]
	v_pk_fma_f32 v[180:181], v[156:157], v[96:97], v[180:181] op_sel:[0,0,0] op_sel_hi:[1,0,1]
	v_pk_fma_f32 v[182:183], v[156:157], v[98:99], v[182:183] op_sel:[0,0,0] op_sel_hi:[1,0,1]
	v_pk_fma_f32 v[184:185], v[156:157], v[100:101], v[184:185] op_sel:[0,0,0] op_sel_hi:[1,0,1]
	v_pk_fma_f32 v[186:187], v[156:157], v[102:103], v[186:187] op_sel:[0,0,0] op_sel_hi:[1,0,1]
	v_pk_fma_f32 v[188:189], v[156:157], v[104:105], v[188:189] op_sel:[0,0,0] op_sel_hi:[1,0,1]
	v_pk_fma_f32 v[190:191], v[156:157], v[106:107], v[190:191] op_sel:[0,0,0] op_sel_hi:[1,0,1]
	v_pk_fma_f32 v[192:193], v[156:157], v[110:111], v[192:193] op_sel:[0,1,0] op_sel_hi:[1,1,1]
	v_pk_fma_f32 v[194:195], v[156:157], v[116:117], v[194:195] op_sel:[0,1,0] op_sel_hi:[1,1,1]
	v_pk_fma_f32 v[196:197], v[156:157], v[122:123], v[196:197] op_sel:[0,1,0] op_sel_hi:[1,1,1]
	v_pk_fma_f32 v[198:199], v[156:157], v[126:127], v[198:199] op_sel:[0,1,0] op_sel_hi:[1,1,1]
	v_pk_fma_f32 v[200:201], v[156:157], v[136:137], v[200:201] op_sel:[0,1,0] op_sel_hi:[1,1,1]
	v_pk_fma_f32 v[202:203], v[156:157], v[138:139], v[202:203] op_sel:[0,1,0] op_sel_hi:[1,1,1]
	v_pk_fma_f32 v[204:205], v[156:157], v[140:141], v[204:205] op_sel:[0,1,0] op_sel_hi:[1,1,1]
	v_pk_fma_f32 v[206:207], v[156:157], v[142:143], v[90:91] op_sel:[0,1,1] op_sel_hi:[1,1,1]
	ds_read2st64_b32 v[154:155], v53 offset0:40 offset1:48
	s_waitcnt lgkmcnt(6)
	v_pk_fma_f32 v[178:179], v[158:159], v[92:93], v[178:179] op_sel:[0,1,0] op_sel_hi:[1,1,1]
	v_pk_fma_f32 v[180:181], v[158:159], v[94:95], v[180:181] op_sel:[0,1,0] op_sel_hi:[1,1,1]
	v_pk_fma_f32 v[182:183], v[158:159], v[96:97], v[182:183] op_sel:[0,1,0] op_sel_hi:[1,1,1]
	v_pk_fma_f32 v[184:185], v[158:159], v[98:99], v[184:185] op_sel:[0,1,0] op_sel_hi:[1,1,1]
	v_pk_fma_f32 v[186:187], v[158:159], v[100:101], v[186:187] op_sel:[0,1,0] op_sel_hi:[1,1,1]
	v_pk_fma_f32 v[188:189], v[158:159], v[102:103], v[188:189] op_sel:[0,1,0] op_sel_hi:[1,1,1]
	v_pk_fma_f32 v[190:191], v[158:159], v[104:105], v[190:191] op_sel:[0,1,0] op_sel_hi:[1,1,1]
	v_pk_fma_f32 v[192:193], v[158:159], v[108:109], v[192:193] op_sel:[0,0,0] op_sel_hi:[1,0,1]
	v_pk_fma_f32 v[194:195], v[158:159], v[114:115], v[194:195] op_sel:[0,0,0] op_sel_hi:[1,0,1]
	v_pk_fma_f32 v[196:197], v[158:159], v[120:121], v[196:197] op_sel:[0,0,0] op_sel_hi:[1,0,1]
	v_pk_fma_f32 v[198:199], v[158:159], v[126:127], v[198:199] op_sel:[0,0,0] op_sel_hi:[1,0,1]
	v_pk_fma_f32 v[200:201], v[158:159], v[136:137], v[200:201] op_sel:[0,0,0] op_sel_hi:[1,0,1]
	v_pk_fma_f32 v[202:203], v[158:159], v[138:139], v[202:203] op_sel:[0,0,0] op_sel_hi:[1,0,1]
	v_pk_fma_f32 v[204:205], v[158:159], v[140:141], v[204:205] op_sel:[0,0,0] op_sel_hi:[1,0,1]
	v_pk_fma_f32 v[206:207], v[158:159], v[142:143], v[206:207] op_sel:[0,0,0] op_sel_hi:[1,0,1]
	ds_read2st64_b32 v[156:157], v53 offset0:48 offset1:56
	s_waitcnt lgkmcnt(6)
; #define LAS __attribute__((address_space(3)))
;     static __device__ __forceinline__ void run(float (&acc)[32], const float (&w)[31], const LAS float* us) {
;         const float v = us[J * 512];
;         constexpr int TLO = (J - 30 > 0) ? J - 30 : 0, THI = (J < 31) ? J : 31;
; #pragma unroll
;         for (int t = TLO; t <= THI; ++t) acc[t] += v * w[J - t];
;         if constexpr (J + 1 < 62) CfLds<J + 1>::run(acc, w, us);
;     }
; __device__ __forceinline__ void cf_prompt_items(LAS unsigned char* lds, const bf16_t* PROJ, int it0, int itstride, int nitems, const float* cw, const float* cb, bf16_t* CONVOUT, float* pcfc) {
;     ...
;         float acc[32];
; #pragma unroll
;         for (int t = 0; t < 32; ++t) acc[t] = bias;
;         CfLds<0>::run(acc, wv, Us + tid);
	v_pk_fma_f32 v[178:179], v[144:145], v[92:93], v[178:179] op_sel:[0,0,0] op_sel_hi:[1,0,1]
	v_pk_fma_f32 v[180:181], v[144:145], v[94:95], v[180:181] op_sel:[0,0,0] op_sel_hi:[1,0,1]
	v_pk_fma_f32 v[182:183], v[144:145], v[96:97], v[182:183] op_sel:[0,0,0] op_sel_hi:[1,0,1]
	v_pk_fma_f32 v[184:185], v[144:145], v[98:99], v[184:185] op_sel:[0,0,0] op_sel_hi:[1,0,1]
	v_pk_fma_f32 v[186:187], v[144:145], v[100:101], v[186:187] op_sel:[0,0,0] op_sel_hi:[1,0,1]
	v_pk_fma_f32 v[188:189], v[144:145], v[102:103], v[188:189] op_sel:[0,0,0] op_sel_hi:[1,0,1]
	v_pk_fma_f32 v[190:191], v[144:145], v[104:105], v[190:191] op_sel:[0,0,0] op_sel_hi:[1,0,1]
	v_pk_fma_f32 v[192:193], v[144:145], v[106:107], v[192:193] op_sel:[0,0,0] op_sel_hi:[1,0,1]
	v_pk_fma_f32 v[194:195], v[144:145], v[110:111], v[194:195] op_sel:[0,1,0] op_sel_hi:[1,1,1]
	v_pk_fma_f32 v[196:197], v[144:145], v[116:117], v[196:197] op_sel:[0,1,0] op_sel_hi:[1,1,1]
	v_pk_fma_f32 v[198:199], v[144:145], v[122:123], v[198:199] op_sel:[0,1,0] op_sel_hi:[1,1,1]
	v_pk_fma_f32 v[200:201], v[144:145], v[126:127], v[200:201] op_sel:[0,1,0] op_sel_hi:[1,1,1]
	v_pk_fma_f32 v[202:203], v[144:145], v[136:137], v[202:203] op_sel:[0,1,0] op_sel_hi:[1,1,1]
	v_pk_fma_f32 v[204:205], v[144:145], v[138:139], v[204:205] op_sel:[0,1,0] op_sel_hi:[1,1,1]
	v_pk_fma_f32 v[206:207], v[144:145], v[140:141], v[206:207] op_sel:[0,1,0] op_sel_hi:[1,1,1]
	ds_read2st64_b32 v[158:159], v53 offset0:56 offset1:64
	s_waitcnt lgkmcnt(6)
	v_pk_fma_f32 v[180:181], v[146:147], v[92:93], v[180:181] op_sel:[0,1,0] op_sel_hi:[1,1,1]
	v_pk_fma_f32 v[182:183], v[146:147], v[94:95], v[182:183] op_sel:[0,1,0] op_sel_hi:[1,1,1]
	v_pk_fma_f32 v[184:185], v[146:147], v[96:97], v[184:185] op_sel:[0,1,0] op_sel_hi:[1,1,1]
	v_pk_fma_f32 v[186:187], v[146:147], v[98:99], v[186:187] op_sel:[0,1,0] op_sel_hi:[1,1,1]
	v_pk_fma_f32 v[188:189], v[146:147], v[100:101], v[188:189] op_sel:[0,1,0] op_sel_hi:[1,1,1]
	v_pk_fma_f32 v[190:191], v[146:147], v[102:103], v[190:191] op_sel:[0,1,0] op_sel_hi:[1,1,1]
	v_pk_fma_f32 v[192:193], v[146:147], v[104:105], v[192:193] op_sel:[0,1,0] op_sel_hi:[1,1,1]
	v_pk_fma_f32 v[194:195], v[146:147], v[108:109], v[194:195] op_sel:[0,0,0] op_sel_hi:[1,0,1]
	v_pk_fma_f32 v[196:197], v[146:147], v[114:115], v[196:197] op_sel:[0,0,0] op_sel_hi:[1,0,1]
	v_pk_fma_f32 v[198:199], v[146:147], v[120:121], v[198:199] op_sel:[0,0,0] op_sel_hi:[1,0,1]
	v_pk_fma_f32 v[200:201], v[146:147], v[126:127], v[200:201] op_sel:[0,0,0] op_sel_hi:[1,0,1]
	v_pk_fma_f32 v[202:203], v[146:147], v[136:137], v[202:203] op_sel:[0,0,0] op_sel_hi:[1,0,1]
	v_pk_fma_f32 v[204:205], v[146:147], v[138:139], v[204:205] op_sel:[0,0,0] op_sel_hi:[1,0,1]
	v_pk_fma_f32 v[206:207], v[146:147], v[140:141], v[206:207] op_sel:[0,0,0] op_sel_hi:[1,0,1]
	ds_read2st64_b32 v[144:145], v53 offset0:64 offset1:72
	s_waitcnt lgkmcnt(6)
	v_pk_fma_f32 v[180:181], v[148:149], v[92:93], v[180:181] op_sel:[0,0,0] op_sel_hi:[1,0,1]
	v_pk_fma_f32 v[182:183], v[148:149], v[94:95], v[182:183] op_sel:[0,0,0] op_sel_hi:[1,0,1]
	v_pk_fma_f32 v[184:185], v[148:149], v[96:97], v[184:185] op_sel:[0,0,0] op_sel_hi:[1,0,1]
	v_pk_fma_f32 v[186:187], v[148:149], v[98:99], v[186:187] op_sel:[0,0,0] op_sel_hi:[1,0,1]
	v_pk_fma_f32 v[188:189], v[148:149], v[100:101], v[188:189] op_sel:[0,0,0] op_sel_hi:[1,0,1]
	v_pk_fma_f32 v[190:191], v[148:149], v[102:103], v[190:191] op_sel:[0,0,0] op_sel_hi:[1,0,1]
	v_pk_fma_f32 v[192:193], v[148:149], v[104:105], v[192:193] op_sel:[0,0,0] op_sel_hi:[1,0,1]
	v_pk_fma_f32 v[194:195], v[148:149], v[106:107], v[194:195] op_sel:[0,0,0] op_sel_hi:[1,0,1]
	v_pk_fma_f32 v[196:197], v[148:149], v[110:111], v[196:197] op_sel:[0,1,0] op_sel_hi:[1,1,1]
	v_pk_fma_f32 v[198:199], v[148:149], v[116:117], v[198:199] op_sel:[0,1,0] op_sel_hi:[1,1,1]
	v_pk_fma_f32 v[200:201], v[148:149], v[122:123], v[200:201] op_sel:[0,1,0] op_sel_hi:[1,1,1]
	v_pk_fma_f32 v[202:203], v[148:149], v[126:127], v[202:203] op_sel:[0,1,0] op_sel_hi:[1,1,1]
	v_pk_fma_f32 v[204:205], v[148:149], v[136:137], v[204:205] op_sel:[0,1,0] op_sel_hi:[1,1,1]
	v_pk_fma_f32 v[206:207], v[148:149], v[138:139], v[206:207] op_sel:[0,1,0] op_sel_hi:[1,1,1]
	ds_read2st64_b32 v[146:147], v53 offset0:72 offset1:80
	s_waitcnt lgkmcnt(6)
	v_pk_fma_f32 v[182:183], v[150:151], v[92:93], v[182:183] op_sel:[0,1,0] op_sel_hi:[1,1,1]
	v_pk_fma_f32 v[184:185], v[150:151], v[94:95], v[184:185] op_sel:[0,1,0] op_sel_hi:[1,1,1]
	v_pk_fma_f32 v[186:187], v[150:151], v[96:97], v[186:187] op_sel:[0,1,0] op_sel_hi:[1,1,1]
	v_pk_fma_f32 v[188:189], v[150:151], v[98:99], v[188:189] op_sel:[0,1,0] op_sel_hi:[1,1,1]
	v_pk_fma_f32 v[190:191], v[150:151], v[100:101], v[190:191] op_sel:[0,1,0] op_sel_hi:[1,1,1]
	v_pk_fma_f32 v[192:193], v[150:151], v[102:103], v[192:193] op_sel:[0,1,0] op_sel_hi:[1,1,1]
	v_pk_fma_f32 v[194:195], v[150:151], v[104:105], v[194:195] op_sel:[0,1,0] op_sel_hi:[1,1,1]
	v_pk_fma_f32 v[196:197], v[150:151], v[108:109], v[196:197] op_sel:[0,0,0] op_sel_hi:[1,0,1]
	v_pk_fma_f32 v[198:199], v[150:151], v[114:115], v[198:199] op_sel:[0,0,0] op_sel_hi:[1,0,1]
	v_pk_fma_f32 v[200:201], v[150:151], v[120:121], v[200:201] op_sel:[0,0,0] op_sel_hi:[1,0,1]
	v_pk_fma_f32 v[202:203], v[150:151], v[126:127], v[202:203] op_sel:[0,0,0] op_sel_hi:[1,0,1]
	v_pk_fma_f32 v[204:205], v[150:151], v[136:137], v[204:205] op_sel:[0,0,0] op_sel_hi:[1,0,1]
	v_pk_fma_f32 v[206:207], v[150:151], v[138:139], v[206:207] op_sel:[0,0,0] op_sel_hi:[1,0,1]
	ds_read2st64_b32 v[148:149], v53 offset0:80 offset1:88
	s_waitcnt lgkmcnt(6)
; #define LAS __attribute__((address_space(3)))
;     static __device__ __forceinline__ void run(float (&acc)[32], const float (&w)[31], const LAS float* us) {
;         const float v = us[J * 512];
;         constexpr int TLO = (J - 30 > 0) ? J - 30 : 0, THI = (J < 31) ? J : 31;
; #pragma unroll
;         for (int t = TLO; t <= THI; ++t) acc[t] += v * w[J - t];
;         if constexpr (J + 1 < 62) CfLds<J + 1>::run(acc, w, us);
;     }
; __device__ __forceinline__ void cf_prompt_items(LAS unsigned char* lds, const bf16_t* PROJ, int it0, int itstride, int nitems, const float* cw, const float* cb, bf16_t* CONVOUT, float* pcfc) {
;     ...
;         float acc[32];
; #pragma unroll
;         for (int t = 0; t < 32; ++t) acc[t] = bias;
;         CfLds<0>::run(acc, wv, Us + tid);
	v_pk_fma_f32 v[182:183], v[152:153], v[92:93], v[182:183] op_sel:[0,0,0] op_sel_hi:[1,0,1]
	v_pk_fma_f32 v[184:185], v[152:153], v[94:95], v[184:185] op_sel:[0,0,0] op_sel_hi:[1,0,1]
	v_pk_fma_f32 v[186:187], v[152:153], v[96:97], v[186:187] op_sel:[0,0,0] op_sel_hi:[1,0,1]
	v_pk_fma_f32 v[188:189], v[152:153], v[98:99], v[188:189] op_sel:[0,0,0] op_sel_hi:[1,0,1]
	v_pk_fma_f32 v[190:191], v[152:153], v[100:101], v[190:191] op_sel:[0,0,0] op_sel_hi:[1,0,1]
	v_pk_fma_f32 v[192:193], v[152:153], v[102:103], v[192:193] op_sel:[0,0,0] op_sel_hi:[1,0,1]
	v_pk_fma_f32 v[194:195], v[152:153], v[104:105], v[194:195] op_sel:[0,0,0] op_sel_hi:[1,0,1]
	v_pk_fma_f32 v[196:197], v[152:153], v[106:107], v[196:197] op_sel:[0,0,0] op_sel_hi:[1,0,1]
	v_pk_fma_f32 v[198:199], v[152:153], v[110:111], v[198:199] op_sel:[0,1,0] op_sel_hi:[1,1,1]
	v_pk_fma_f32 v[200:201], v[152:153], v[116:117], v[200:201] op_sel:[0,1,0] op_sel_hi:[1,1,1]
	v_pk_fma_f32 v[202:203], v[152:153], v[122:123], v[202:203] op_sel:[0,1,0] op_sel_hi:[1,1,1]
	v_pk_fma_f32 v[204:205], v[152:153], v[126:127], v[204:205] op_sel:[0,1,0] op_sel_hi:[1,1,1]
	v_pk_fma_f32 v[206:207], v[152:153], v[136:137], v[206:207] op_sel:[0,1,0] op_sel_hi:[1,1,1]
	ds_read2st64_b32 v[150:151], v53 offset0:88 offset1:96
	s_waitcnt lgkmcnt(6)
	v_pk_fma_f32 v[184:185], v[154:155], v[92:93], v[184:185] op_sel:[0,1,0] op_sel_hi:[1,1,1]
	v_pk_fma_f32 v[186:187], v[154:155], v[94:95], v[186:187] op_sel:[0,1,0] op_sel_hi:[1,1,1]
	v_pk_fma_f32 v[188:189], v[154:155], v[96:97], v[188:189] op_sel:[0,1,0] op_sel_hi:[1,1,1]
	v_pk_fma_f32 v[190:191], v[154:155], v[98:99], v[190:191] op_sel:[0,1,0] op_sel_hi:[1,1,1]
	v_pk_fma_f32 v[192:193], v[154:155], v[100:101], v[192:193] op_sel:[0,1,0] op_sel_hi:[1,1,1]
	v_pk_fma_f32 v[194:195], v[154:155], v[102:103], v[194:195] op_sel:[0,1,0] op_sel_hi:[1,1,1]
	v_pk_fma_f32 v[196:197], v[154:155], v[104:105], v[196:197] op_sel:[0,1,0] op_sel_hi:[1,1,1]
	v_pk_fma_f32 v[198:199], v[154:155], v[108:109], v[198:199] op_sel:[0,0,0] op_sel_hi:[1,0,1]
	v_pk_fma_f32 v[200:201], v[154:155], v[114:115], v[200:201] op_sel:[0,0,0] op_sel_hi:[1,0,1]
	v_pk_fma_f32 v[202:203], v[154:155], v[120:121], v[202:203] op_sel:[0,0,0] op_sel_hi:[1,0,1]
	v_pk_fma_f32 v[204:205], v[154:155], v[126:127], v[204:205] op_sel:[0,0,0] op_sel_hi:[1,0,1]
	v_pk_fma_f32 v[206:207], v[154:155], v[136:137], v[206:207] op_sel:[0,0,0] op_sel_hi:[1,0,1]
	ds_read2st64_b32 v[152:153], v53 offset0:96 offset1:104
	s_waitcnt lgkmcnt(6)
	v_pk_fma_f32 v[184:185], v[156:157], v[92:93], v[184:185] op_sel:[0,0,0] op_sel_hi:[1,0,1]
	v_pk_fma_f32 v[186:187], v[156:157], v[94:95], v[186:187] op_sel:[0,0,0] op_sel_hi:[1,0,1]
	v_pk_fma_f32 v[188:189], v[156:157], v[96:97], v[188:189] op_sel:[0,0,0] op_sel_hi:[1,0,1]
	v_pk_fma_f32 v[190:191], v[156:157], v[98:99], v[190:191] op_sel:[0,0,0] op_sel_hi:[1,0,1]
	v_pk_fma_f32 v[192:193], v[156:157], v[100:101], v[192:193] op_sel:[0,0,0] op_sel_hi:[1,0,1]
	v_pk_fma_f32 v[194:195], v[156:157], v[102:103], v[194:195] op_sel:[0,0,0] op_sel_hi:[1,0,1]
	v_pk_fma_f32 v[196:197], v[156:157], v[104:105], v[196:197] op_sel:[0,0,0] op_sel_hi:[1,0,1]
	v_pk_fma_f32 v[198:199], v[156:157], v[106:107], v[198:199] op_sel:[0,0,0] op_sel_hi:[1,0,1]
	v_pk_fma_f32 v[200:201], v[156:157], v[110:111], v[200:201] op_sel:[0,1,0] op_sel_hi:[1,1,1]
	v_pk_fma_f32 v[202:203], v[156:157], v[116:117], v[202:203] op_sel:[0,1,0] op_sel_hi:[1,1,1]
	v_pk_fma_f32 v[204:205], v[156:157], v[122:123], v[204:205] op_sel:[0,1,0] op_sel_hi:[1,1,1]
	v_pk_fma_f32 v[206:207], v[156:157], v[126:127], v[206:207] op_sel:[0,1,0] op_sel_hi:[1,1,1]
	ds_read2st64_b32 v[154:155], v53 offset0:104 offset1:112
	s_waitcnt lgkmcnt(6)
	v_pk_fma_f32 v[186:187], v[158:159], v[92:93], v[186:187] op_sel:[0,1,0] op_sel_hi:[1,1,1]
	v_pk_fma_f32 v[188:189], v[158:159], v[94:95], v[188:189] op_sel:[0,1,0] op_sel_hi:[1,1,1]
	v_pk_fma_f32 v[190:191], v[158:159], v[96:97], v[190:191] op_sel:[0,1,0] op_sel_hi:[1,1,1]
	v_pk_fma_f32 v[192:193], v[158:159], v[98:99], v[192:193] op_sel:[0,1,0] op_sel_hi:[1,1,1]
	v_pk_fma_f32 v[194:195], v[158:159], v[100:101], v[194:195] op_sel:[0,1,0] op_sel_hi:[1,1,1]
	v_pk_fma_f32 v[196:197], v[158:159], v[102:103], v[196:197] op_sel:[0,1,0] op_sel_hi:[1,1,1]
	v_pk_fma_f32 v[198:199], v[158:159], v[104:105], v[198:199] op_sel:[0,1,0] op_sel_hi:[1,1,1]
	v_pk_fma_f32 v[200:201], v[158:159], v[108:109], v[200:201] op_sel:[0,0,0] op_sel_hi:[1,0,1]
	v_pk_fma_f32 v[202:203], v[158:159], v[114:115], v[202:203] op_sel:[0,0,0] op_sel_hi:[1,0,1]
	v_pk_fma_f32 v[204:205], v[158:159], v[120:121], v[204:205] op_sel:[0,0,0] op_sel_hi:[1,0,1]
	v_pk_fma_f32 v[206:207], v[158:159], v[126:127], v[206:207] op_sel:[0,0,0] op_sel_hi:[1,0,1]
	ds_read2st64_b32 v[156:157], v53 offset0:112 offset1:120
	s_waitcnt lgkmcnt(6)
	v_pk_fma_f32 v[186:187], v[144:145], v[92:93], v[186:187] op_sel:[0,0,0] op_sel_hi:[1,0,1]
	v_pk_fma_f32 v[188:189], v[144:145], v[94:95], v[188:189] op_sel:[0,0,0] op_sel_hi:[1,0,1]
	v_pk_fma_f32 v[190:191], v[144:145], v[96:97], v[190:191] op_sel:[0,0,0] op_sel_hi:[1,0,1]
	v_pk_fma_f32 v[192:193], v[144:145], v[98:99], v[192:193] op_sel:[0,0,0] op_sel_hi:[1,0,1]
	v_pk_fma_f32 v[194:195], v[144:145], v[100:101], v[194:195] op_sel:[0,0,0] op_sel_hi:[1,0,1]
	v_pk_fma_f32 v[196:197], v[144:145], v[102:103], v[196:197] op_sel:[0,0,0] op_sel_hi:[1,0,1]
	v_pk_fma_f32 v[198:199], v[144:145], v[104:105], v[198:199] op_sel:[0,0,0] op_sel_hi:[1,0,1]
	v_pk_fma_f32 v[200:201], v[144:145], v[106:107], v[200:201] op_sel:[0,0,0] op_sel_hi:[1,0,1]
	v_pk_fma_f32 v[202:203], v[144:145], v[110:111], v[202:203] op_sel:[0,1,0] op_sel_hi:[1,1,1]
	v_pk_fma_f32 v[204:205], v[144:145], v[116:117], v[204:205] op_sel:[0,1,0] op_sel_hi:[1,1,1]
	v_pk_fma_f32 v[206:207], v[144:145], v[122:123], v[206:207] op_sel:[0,1,0] op_sel_hi:[1,1,1]
	ds_read2st64_b32 v[158:159], v53 offset0:120 offset1:128
	s_waitcnt lgkmcnt(6)
; #define LAS __attribute__((address_space(3)))
;     static __device__ __forceinline__ void run(float (&acc)[32], const float (&w)[31], const LAS float* us) {
;         const float v = us[J * 512];
;         constexpr int TLO = (J - 30 > 0) ? J - 30 : 0, THI = (J < 31) ? J : 31;
; #pragma unroll
;         for (int t = TLO; t <= THI; ++t) acc[t] += v * w[J - t];
;         if constexpr (J + 1 < 62) CfLds<J + 1>::run(acc, w, us);
;     }
; __device__ __forceinline__ void cf_prompt_items(LAS unsigned char* lds, const bf16_t* PROJ, int it0, int itstride, int nitems, const float* cw, const float* cb, bf16_t* CONVOUT, float* pcfc) {
;     ...
;         float acc[32];
; #pragma unroll
;         for (int t = 0; t < 32; ++t) acc[t] = bias;
;         CfLds<0>::run(acc, wv, Us + tid);
	v_pk_fma_f32 v[188:189], v[146:147], v[92:93], v[188:189] op_sel:[0,1,0] op_sel_hi:[1,1,1]
	v_pk_fma_f32 v[190:191], v[146:147], v[94:95], v[190:191] op_sel:[0,1,0] op_sel_hi:[1,1,1]
	v_pk_fma_f32 v[192:193], v[146:147], v[96:97], v[192:193] op_sel:[0,1,0] op_sel_hi:[1,1,1]
	v_pk_fma_f32 v[194:195], v[146:147], v[98:99], v[194:195] op_sel:[0,1,0] op_sel_hi:[1,1,1]
	v_pk_fma_f32 v[196:197], v[146:147], v[100:101], v[196:197] op_sel:[0,1,0] op_sel_hi:[1,1,1]
	v_pk_fma_f32 v[198:199], v[146:147], v[102:103], v[198:199] op_sel:[0,1,0] op_sel_hi:[1,1,1]
	v_pk_fma_f32 v[200:201], v[146:147], v[104:105], v[200:201] op_sel:[0,1,0] op_sel_hi:[1,1,1]
	v_pk_fma_f32 v[202:203], v[146:147], v[108:109], v[202:203] op_sel:[0,0,0] op_sel_hi:[1,0,1]
	v_pk_fma_f32 v[204:205], v[146:147], v[114:115], v[204:205] op_sel:[0,0,0] op_sel_hi:[1,0,1]
	v_pk_fma_f32 v[206:207], v[146:147], v[120:121], v[206:207] op_sel:[0,0,0] op_sel_hi:[1,0,1]
	ds_read2st64_b32 v[144:145], v53 offset0:128 offset1:136
	s_waitcnt lgkmcnt(6)
	v_pk_fma_f32 v[188:189], v[148:149], v[92:93], v[188:189] op_sel:[0,0,0] op_sel_hi:[1,0,1]
	v_pk_fma_f32 v[190:191], v[148:149], v[94:95], v[190:191] op_sel:[0,0,0] op_sel_hi:[1,0,1]
	v_pk_fma_f32 v[192:193], v[148:149], v[96:97], v[192:193] op_sel:[0,0,0] op_sel_hi:[1,0,1]
	v_pk_fma_f32 v[194:195], v[148:149], v[98:99], v[194:195] op_sel:[0,0,0] op_sel_hi:[1,0,1]
	v_pk_fma_f32 v[196:197], v[148:149], v[100:101], v[196:197] op_sel:[0,0,0] op_sel_hi:[1,0,1]
	v_pk_fma_f32 v[198:199], v[148:149], v[102:103], v[198:199] op_sel:[0,0,0] op_sel_hi:[1,0,1]
	v_pk_fma_f32 v[200:201], v[148:149], v[104:105], v[200:201] op_sel:[0,0,0] op_sel_hi:[1,0,1]
	v_pk_fma_f32 v[202:203], v[148:149], v[106:107], v[202:203] op_sel:[0,0,0] op_sel_hi:[1,0,1]
	v_pk_fma_f32 v[204:205], v[148:149], v[110:111], v[204:205] op_sel:[0,1,0] op_sel_hi:[1,1,1]
	v_pk_fma_f32 v[206:207], v[148:149], v[116:117], v[206:207] op_sel:[0,1,0] op_sel_hi:[1,1,1]
	ds_read2st64_b32 v[146:147], v53 offset0:136 offset1:144
	s_waitcnt lgkmcnt(6)
	v_pk_fma_f32 v[190:191], v[150:151], v[92:93], v[190:191] op_sel:[0,1,0] op_sel_hi:[1,1,1]
	v_pk_fma_f32 v[192:193], v[150:151], v[94:95], v[192:193] op_sel:[0,1,0] op_sel_hi:[1,1,1]
	v_pk_fma_f32 v[194:195], v[150:151], v[96:97], v[194:195] op_sel:[0,1,0] op_sel_hi:[1,1,1]
	v_pk_fma_f32 v[196:197], v[150:151], v[98:99], v[196:197] op_sel:[0,1,0] op_sel_hi:[1,1,1]
	v_pk_fma_f32 v[198:199], v[150:151], v[100:101], v[198:199] op_sel:[0,1,0] op_sel_hi:[1,1,1]
	v_pk_fma_f32 v[200:201], v[150:151], v[102:103], v[200:201] op_sel:[0,1,0] op_sel_hi:[1,1,1]
	v_pk_fma_f32 v[202:203], v[150:151], v[104:105], v[202:203] op_sel:[0,1,0] op_sel_hi:[1,1,1]
	v_pk_fma_f32 v[204:205], v[150:151], v[108:109], v[204:205] op_sel:[0,0,0] op_sel_hi:[1,0,1]
	v_pk_fma_f32 v[206:207], v[150:151], v[114:115], v[206:207] op_sel:[0,0,0] op_sel_hi:[1,0,1]
	ds_read2st64_b32 v[148:149], v53 offset0:144 offset1:152
	s_waitcnt lgkmcnt(6)
	v_pk_fma_f32 v[190:191], v[152:153], v[92:93], v[190:191] op_sel:[0,0,0] op_sel_hi:[1,0,1]
	v_pk_fma_f32 v[192:193], v[152:153], v[94:95], v[192:193] op_sel:[0,0,0] op_sel_hi:[1,0,1]
	v_pk_fma_f32 v[194:195], v[152:153], v[96:97], v[194:195] op_sel:[0,0,0] op_sel_hi:[1,0,1]
	v_pk_fma_f32 v[196:197], v[152:153], v[98:99], v[196:197] op_sel:[0,0,0] op_sel_hi:[1,0,1]
	v_pk_fma_f32 v[198:199], v[152:153], v[100:101], v[198:199] op_sel:[0,0,0] op_sel_hi:[1,0,1]
	v_pk_fma_f32 v[200:201], v[152:153], v[102:103], v[200:201] op_sel:[0,0,0] op_sel_hi:[1,0,1]
	v_pk_fma_f32 v[202:203], v[152:153], v[104:105], v[202:203] op_sel:[0,0,0] op_sel_hi:[1,0,1]
	v_pk_fma_f32 v[204:205], v[152:153], v[106:107], v[204:205] op_sel:[0,0,0] op_sel_hi:[1,0,1]
	v_pk_fma_f32 v[206:207], v[152:153], v[110:111], v[206:207] op_sel:[0,1,0] op_sel_hi:[1,1,1]
	ds_read2st64_b32 v[150:151], v53 offset0:152 offset1:160
	s_waitcnt lgkmcnt(6)
	v_pk_fma_f32 v[192:193], v[154:155], v[92:93], v[192:193] op_sel:[0,1,0] op_sel_hi:[1,1,1]
	v_pk_fma_f32 v[194:195], v[154:155], v[94:95], v[194:195] op_sel:[0,1,0] op_sel_hi:[1,1,1]
	v_pk_fma_f32 v[196:197], v[154:155], v[96:97], v[196:197] op_sel:[0,1,0] op_sel_hi:[1,1,1]
	v_pk_fma_f32 v[198:199], v[154:155], v[98:99], v[198:199] op_sel:[0,1,0] op_sel_hi:[1,1,1]
	v_pk_fma_f32 v[200:201], v[154:155], v[100:101], v[200:201] op_sel:[0,1,0] op_sel_hi:[1,1,1]
	v_pk_fma_f32 v[202:203], v[154:155], v[102:103], v[202:203] op_sel:[0,1,0] op_sel_hi:[1,1,1]
	v_pk_fma_f32 v[204:205], v[154:155], v[104:105], v[204:205] op_sel:[0,1,0] op_sel_hi:[1,1,1]
	v_pk_fma_f32 v[206:207], v[154:155], v[108:109], v[206:207] op_sel:[0,0,0] op_sel_hi:[1,0,1]
	ds_read2st64_b32 v[152:153], v53 offset0:160 offset1:168
	s_waitcnt lgkmcnt(6)
	v_pk_fma_f32 v[192:193], v[156:157], v[92:93], v[192:193] op_sel:[0,0,0] op_sel_hi:[1,0,1]
	v_pk_fma_f32 v[194:195], v[156:157], v[94:95], v[194:195] op_sel:[0,0,0] op_sel_hi:[1,0,1]
	v_pk_fma_f32 v[196:197], v[156:157], v[96:97], v[196:197] op_sel:[0,0,0] op_sel_hi:[1,0,1]
	v_pk_fma_f32 v[198:199], v[156:157], v[98:99], v[198:199] op_sel:[0,0,0] op_sel_hi:[1,0,1]
	v_pk_fma_f32 v[200:201], v[156:157], v[100:101], v[200:201] op_sel:[0,0,0] op_sel_hi:[1,0,1]
	v_pk_fma_f32 v[202:203], v[156:157], v[102:103], v[202:203] op_sel:[0,0,0] op_sel_hi:[1,0,1]
	v_pk_fma_f32 v[204:205], v[156:157], v[104:105], v[204:205] op_sel:[0,0,0] op_sel_hi:[1,0,1]
	v_pk_fma_f32 v[206:207], v[156:157], v[106:107], v[206:207] op_sel:[0,0,0] op_sel_hi:[1,0,1]
	ds_read2st64_b32 v[154:155], v53 offset0:168 offset1:176
	s_waitcnt lgkmcnt(6)
; #define LAS __attribute__((address_space(3)))
;     static __device__ __forceinline__ void run(float (&acc)[32], const float (&w)[31], const LAS float* us) {
;         const float v = us[J * 512];
;         constexpr int TLO = (J - 30 > 0) ? J - 30 : 0, THI = (J < 31) ? J : 31;
; #pragma unroll
;         for (int t = TLO; t <= THI; ++t) acc[t] += v * w[J - t];
;         if constexpr (J + 1 < 62) CfLds<J + 1>::run(acc, w, us);
;     }
; __device__ __forceinline__ void cf_prompt_items(LAS unsigned char* lds, const bf16_t* PROJ, int it0, int itstride, int nitems, const float* cw, const float* cb, bf16_t* CONVOUT, float* pcfc) {
;     ...
;         float acc[32];
; #pragma unroll
;         for (int t = 0; t < 32; ++t) acc[t] = bias;
;         CfLds<0>::run(acc, wv, Us + tid);
	v_pk_fma_f32 v[194:195], v[158:159], v[92:93], v[194:195] op_sel:[0,1,0] op_sel_hi:[1,1,1]
	v_pk_fma_f32 v[196:197], v[158:159], v[94:95], v[196:197] op_sel:[0,1,0] op_sel_hi:[1,1,1]
	v_pk_fma_f32 v[198:199], v[158:159], v[96:97], v[198:199] op_sel:[0,1,0] op_sel_hi:[1,1,1]
	v_pk_fma_f32 v[200:201], v[158:159], v[98:99], v[200:201] op_sel:[0,1,0] op_sel_hi:[1,1,1]
	v_pk_fma_f32 v[202:203], v[158:159], v[100:101], v[202:203] op_sel:[0,1,0] op_sel_hi:[1,1,1]
	v_pk_fma_f32 v[204:205], v[158:159], v[102:103], v[204:205] op_sel:[0,1,0] op_sel_hi:[1,1,1]
	v_pk_fma_f32 v[206:207], v[158:159], v[104:105], v[206:207] op_sel:[0,1,0] op_sel_hi:[1,1,1]
	ds_read2st64_b32 v[156:157], v53 offset0:176 offset1:184
	s_waitcnt lgkmcnt(6)
	v_pk_fma_f32 v[194:195], v[144:145], v[92:93], v[194:195] op_sel:[0,0,0] op_sel_hi:[1,0,1]
	v_pk_fma_f32 v[196:197], v[144:145], v[94:95], v[196:197] op_sel:[0,0,0] op_sel_hi:[1,0,1]
	v_pk_fma_f32 v[198:199], v[144:145], v[96:97], v[198:199] op_sel:[0,0,0] op_sel_hi:[1,0,1]
	v_pk_fma_f32 v[200:201], v[144:145], v[98:99], v[200:201] op_sel:[0,0,0] op_sel_hi:[1,0,1]
	v_pk_fma_f32 v[202:203], v[144:145], v[100:101], v[202:203] op_sel:[0,0,0] op_sel_hi:[1,0,1]
	v_pk_fma_f32 v[204:205], v[144:145], v[102:103], v[204:205] op_sel:[0,0,0] op_sel_hi:[1,0,1]
	v_pk_fma_f32 v[206:207], v[144:145], v[104:105], v[206:207] op_sel:[0,0,0] op_sel_hi:[1,0,1]
	ds_read2st64_b32 v[158:159], v53 offset0:184 offset1:192
	s_waitcnt lgkmcnt(6)
	v_pk_fma_f32 v[196:197], v[146:147], v[92:93], v[196:197] op_sel:[0,1,0] op_sel_hi:[1,1,1]
	v_pk_fma_f32 v[198:199], v[146:147], v[94:95], v[198:199] op_sel:[0,1,0] op_sel_hi:[1,1,1]
	v_pk_fma_f32 v[200:201], v[146:147], v[96:97], v[200:201] op_sel:[0,1,0] op_sel_hi:[1,1,1]
	v_pk_fma_f32 v[202:203], v[146:147], v[98:99], v[202:203] op_sel:[0,1,0] op_sel_hi:[1,1,1]
	v_pk_fma_f32 v[204:205], v[146:147], v[100:101], v[204:205] op_sel:[0,1,0] op_sel_hi:[1,1,1]
	v_pk_fma_f32 v[206:207], v[146:147], v[102:103], v[206:207] op_sel:[0,1,0] op_sel_hi:[1,1,1]
	ds_read2st64_b32 v[144:145], v53 offset0:192 offset1:200
	s_waitcnt lgkmcnt(6)
	v_pk_fma_f32 v[196:197], v[148:149], v[92:93], v[196:197] op_sel:[0,0,0] op_sel_hi:[1,0,1]
	v_pk_fma_f32 v[198:199], v[148:149], v[94:95], v[198:199] op_sel:[0,0,0] op_sel_hi:[1,0,1]
	v_pk_fma_f32 v[200:201], v[148:149], v[96:97], v[200:201] op_sel:[0,0,0] op_sel_hi:[1,0,1]
	v_pk_fma_f32 v[202:203], v[148:149], v[98:99], v[202:203] op_sel:[0,0,0] op_sel_hi:[1,0,1]
	v_pk_fma_f32 v[204:205], v[148:149], v[100:101], v[204:205] op_sel:[0,0,0] op_sel_hi:[1,0,1]
	v_pk_fma_f32 v[206:207], v[148:149], v[102:103], v[206:207] op_sel:[0,0,0] op_sel_hi:[1,0,1]
	ds_read2st64_b32 v[146:147], v53 offset0:200 offset1:208
	s_waitcnt lgkmcnt(6)
	v_pk_fma_f32 v[198:199], v[150:151], v[92:93], v[198:199] op_sel:[0,1,0] op_sel_hi:[1,1,1]
	v_pk_fma_f32 v[200:201], v[150:151], v[94:95], v[200:201] op_sel:[0,1,0] op_sel_hi:[1,1,1]
	v_pk_fma_f32 v[202:203], v[150:151], v[96:97], v[202:203] op_sel:[0,1,0] op_sel_hi:[1,1,1]
	v_pk_fma_f32 v[204:205], v[150:151], v[98:99], v[204:205] op_sel:[0,1,0] op_sel_hi:[1,1,1]
	v_pk_fma_f32 v[206:207], v[150:151], v[100:101], v[206:207] op_sel:[0,1,0] op_sel_hi:[1,1,1]
	ds_read2st64_b32 v[148:149], v53 offset0:208 offset1:216
	s_waitcnt lgkmcnt(6)
	v_pk_fma_f32 v[198:199], v[152:153], v[92:93], v[198:199] op_sel:[0,0,0] op_sel_hi:[1,0,1]
	v_pk_fma_f32 v[200:201], v[152:153], v[94:95], v[200:201] op_sel:[0,0,0] op_sel_hi:[1,0,1]
	v_pk_fma_f32 v[202:203], v[152:153], v[96:97], v[202:203] op_sel:[0,0,0] op_sel_hi:[1,0,1]
	v_pk_fma_f32 v[204:205], v[152:153], v[98:99], v[204:205] op_sel:[0,0,0] op_sel_hi:[1,0,1]
	v_pk_fma_f32 v[206:207], v[152:153], v[100:101], v[206:207] op_sel:[0,0,0] op_sel_hi:[1,0,1]
	ds_read2st64_b32 v[150:151], v53 offset0:216 offset1:224
	s_waitcnt lgkmcnt(6)
	v_pk_fma_f32 v[200:201], v[154:155], v[92:93], v[200:201] op_sel:[0,1,0] op_sel_hi:[1,1,1]
	v_pk_fma_f32 v[202:203], v[154:155], v[94:95], v[202:203] op_sel:[0,1,0] op_sel_hi:[1,1,1]
	v_pk_fma_f32 v[204:205], v[154:155], v[96:97], v[204:205] op_sel:[0,1,0] op_sel_hi:[1,1,1]
	v_pk_fma_f32 v[206:207], v[154:155], v[98:99], v[206:207] op_sel:[0,1,0] op_sel_hi:[1,1,1]
	ds_read2st64_b32 v[152:153], v53 offset0:224 offset1:232
	s_waitcnt lgkmcnt(6)
	v_pk_fma_f32 v[200:201], v[156:157], v[92:93], v[200:201] op_sel:[0,0,0] op_sel_hi:[1,0,1]
	v_pk_fma_f32 v[202:203], v[156:157], v[94:95], v[202:203] op_sel:[0,0,0] op_sel_hi:[1,0,1]
	v_pk_fma_f32 v[204:205], v[156:157], v[96:97], v[204:205] op_sel:[0,0,0] op_sel_hi:[1,0,1]
	v_pk_fma_f32 v[206:207], v[156:157], v[98:99], v[206:207] op_sel:[0,0,0] op_sel_hi:[1,0,1]
	s_waitcnt lgkmcnt(5)
	v_pk_fma_f32 v[202:203], v[158:159], v[92:93], v[202:203] op_sel:[0,1,0] op_sel_hi:[1,1,1]
	v_pk_fma_f32 v[204:205], v[158:159], v[94:95], v[204:205] op_sel:[0,1,0] op_sel_hi:[1,1,1]
	v_pk_fma_f32 v[206:207], v[158:159], v[96:97], v[206:207] op_sel:[0,1,0] op_sel_hi:[1,1,1]
	s_waitcnt lgkmcnt(4)
	v_pk_fma_f32 v[202:203], v[144:145], v[92:93], v[202:203] op_sel:[0,0,0] op_sel_hi:[1,0,1]
	v_pk_fma_f32 v[204:205], v[144:145], v[94:95], v[204:205] op_sel:[0,0,0] op_sel_hi:[1,0,1]
	v_pk_fma_f32 v[206:207], v[144:145], v[96:97], v[206:207] op_sel:[0,0,0] op_sel_hi:[1,0,1]
	s_waitcnt lgkmcnt(3)
; #define LAS __attribute__((address_space(3)))
; __device__ __forceinline__ unsigned f2bf(float f) { unsigned u = __float_as_uint(f); return (u + 0x7fffu + ((u >> 16) & 1u)) >> 16; }
; #define LDS_BARRIER() do { asm volatile("s_waitcnt lgkmcnt(0)" ::: "memory"); __builtin_amdgcn_s_barrier(); asm volatile("" ::: "memory"); } while (0)
; __device__ __forceinline__ void cf_prompt_items(LAS unsigned char* lds, const bf16_t* PROJ, int it0, int itstride, int nitems, const float* cw, const float* cb, bf16_t* CONVOUT, float* pcfc) {
;     ...
;         const int row0 = (it >> 2) * 32, t0 = row0 % SEQ, b = row0 / SEQ, c0 = (it & 3) * 512;
;         float* state_out = (t0 == SEQ - 32) ? pcfc + (size_t)b * 30 * DM : nullptr;
;         float wv[31];
; #pragma unroll
;         for (int i = 0; i < 31; ++i) wv[i] = cw[i * DM + c0 + tid];
;         const float bias = cb[c0 + tid];
; #pragma unroll
;         for (int i = 0; i < 8; ++i) { const int j = w + 8 * i;
;             if (j < 62) { float a[8]; unpack8(av[i], a);
;                 const f32x4 u0 = (f32x4){a[0], a[1], a[2], a[3]}, u1 = (f32x4){a[4], a[5], a[6], a[7]};
;                 *(LAS f32x4*)(Us + j * 512 + lane * 8) = u0; *(LAS f32x4*)(Us + j * 512 + lane * 8 + 4) = u1;
;                 if (state_out && j >= 32) { float* sp = state_out + (size_t)(j - 32) * DM + c0 + lane * 8; *(f32x4*)sp = u0; *(f32x4*)(sp + 4) = u1; } } }
;     ...
;         CfLds<0>::run(acc, wv, Us + tid);
; #pragma unroll
;         for (int t = 0; t < 32; ++t) CONVOUT[(size_t)(row0 + t) * DM + c0 + tid] = (bf16_t)f2bf(acc[t]);
;         LDS_BARRIER();
;     }
	v_pk_fma_f32 v[204:205], v[146:147], v[92:93], v[204:205] op_sel:[0,1,0] op_sel_hi:[1,1,1]
	v_pk_fma_f32 v[206:207], v[146:147], v[94:95], v[206:207] op_sel:[0,1,0] op_sel_hi:[1,1,1]
	s_waitcnt lgkmcnt(2)
	v_pk_fma_f32 v[204:205], v[148:149], v[92:93], v[204:205] op_sel:[0,0,0] op_sel_hi:[1,0,1]
	v_pk_fma_f32 v[206:207], v[148:149], v[94:95], v[206:207] op_sel:[0,0,0] op_sel_hi:[1,0,1]
	s_waitcnt lgkmcnt(1)
	v_pk_fma_f32 v[206:207], v[150:151], v[92:93], v[206:207] op_sel:[0,1,0] op_sel_hi:[1,1,1]
	s_waitcnt lgkmcnt(0)
	v_pk_fma_f32 v[206:207], v[152:153], v[92:93], v[206:207] op_sel:[0,0,0] op_sel_hi:[1,0,1]
	s_add_u32 s0, s0, s6
	s_addc_u32 s1, s1, s7
	s_add_u32 s0, s0, s38
	s_addc_u32 s1, s1, 0
	v_lshlrev_b32_e32 v13, 1, v44
	v_cvt_pk_bf16_f32 v36, v176, v177
	global_store_short v13, v36, s[0:1]
	s_add_u32 s0, s0, 0x1000
	s_addc_u32 s1, s1, 0
	global_store_short_d16_hi v13, v36, s[0:1]
	s_add_u32 s0, s0, 0x1000
	s_addc_u32 s1, s1, 0
	v_cvt_pk_bf16_f32 v37, v178, v179
	global_store_short v13, v37, s[0:1]
	s_add_u32 s0, s0, 0x1000
	s_addc_u32 s1, s1, 0
	global_store_short_d16_hi v13, v37, s[0:1]
	s_add_u32 s0, s0, 0x1000
	s_addc_u32 s1, s1, 0
	v_cvt_pk_bf16_f32 v38, v180, v181
	global_store_short v13, v38, s[0:1]
	s_add_u32 s0, s0, 0x1000
	s_addc_u32 s1, s1, 0
	global_store_short_d16_hi v13, v38, s[0:1]
	s_add_u32 s0, s0, 0x1000
	s_addc_u32 s1, s1, 0
	v_cvt_pk_bf16_f32 v39, v182, v183
	global_store_short v13, v39, s[0:1]
	s_add_u32 s0, s0, 0x1000
	s_addc_u32 s1, s1, 0
	global_store_short_d16_hi v13, v39, s[0:1]
	s_add_u32 s0, s0, 0x1000
	s_addc_u32 s1, s1, 0
	v_cvt_pk_bf16_f32 v36, v184, v185
	global_store_short v13, v36, s[0:1]
	s_add_u32 s0, s0, 0x1000
	s_addc_u32 s1, s1, 0
	global_store_short_d16_hi v13, v36, s[0:1]
	s_add_u32 s0, s0, 0x1000
	s_addc_u32 s1, s1, 0
	v_cvt_pk_bf16_f32 v37, v186, v187
	global_store_short v13, v37, s[0:1]
	s_add_u32 s0, s0, 0x1000
	s_addc_u32 s1, s1, 0
	global_store_short_d16_hi v13, v37, s[0:1]
	s_add_u32 s0, s0, 0x1000
	s_addc_u32 s1, s1, 0
	v_cvt_pk_bf16_f32 v38, v188, v189
	global_store_short v13, v38, s[0:1]
	s_add_u32 s0, s0, 0x1000
	s_addc_u32 s1, s1, 0
	global_store_short_d16_hi v13, v38, s[0:1]
	s_add_u32 s0, s0, 0x1000
	s_addc_u32 s1, s1, 0
	v_cvt_pk_bf16_f32 v39, v190, v191
	global_store_short v13, v39, s[0:1]
	s_add_u32 s0, s0, 0x1000
	s_addc_u32 s1, s1, 0
	global_store_short_d16_hi v13, v39, s[0:1]
	s_add_u32 s0, s0, 0x1000
	s_addc_u32 s1, s1, 0
	v_cvt_pk_bf16_f32 v36, v192, v193
	global_store_short v13, v36, s[0:1]
	s_add_u32 s0, s0, 0x1000
	s_addc_u32 s1, s1, 0
	global_store_short_d16_hi v13, v36, s[0:1]
	s_add_u32 s0, s0, 0x1000
	s_addc_u32 s1, s1, 0
	v_cvt_pk_bf16_f32 v37, v194, v195
	global_store_short v13, v37, s[0:1]
	s_add_u32 s0, s0, 0x1000
	s_addc_u32 s1, s1, 0
	global_store_short_d16_hi v13, v37, s[0:1]
	s_add_u32 s0, s0, 0x1000
	s_addc_u32 s1, s1, 0
	v_cvt_pk_bf16_f32 v38, v196, v197
	global_store_short v13, v38, s[0:1]
	s_add_u32 s0, s0, 0x1000
	s_addc_u32 s1, s1, 0
	global_store_short_d16_hi v13, v38, s[0:1]
	s_add_u32 s0, s0, 0x1000
	s_addc_u32 s1, s1, 0
	v_cvt_pk_bf16_f32 v39, v198, v199
	global_store_short v13, v39, s[0:1]
	s_add_u32 s0, s0, 0x1000
	s_addc_u32 s1, s1, 0
	global_store_short_d16_hi v13, v39, s[0:1]
	s_add_u32 s0, s0, 0x1000
	s_addc_u32 s1, s1, 0
	v_cvt_pk_bf16_f32 v36, v200, v201
	global_store_short v13, v36, s[0:1]
	s_add_u32 s0, s0, 0x1000
	s_addc_u32 s1, s1, 0
	global_store_short_d16_hi v13, v36, s[0:1]
	s_add_u32 s0, s0, 0x1000
	s_addc_u32 s1, s1, 0
	v_cvt_pk_bf16_f32 v37, v202, v203
	global_store_short v13, v37, s[0:1]
	s_add_u32 s0, s0, 0x1000
	s_addc_u32 s1, s1, 0
	global_store_short_d16_hi v13, v37, s[0:1]
	s_add_u32 s0, s0, 0x1000
	s_addc_u32 s1, s1, 0
	v_cvt_pk_bf16_f32 v38, v204, v205
	global_store_short v13, v38, s[0:1]
	s_add_u32 s0, s0, 0x1000
	s_addc_u32 s1, s1, 0
	global_store_short_d16_hi v13, v38, s[0:1]
	s_add_u32 s0, s0, 0x1000
	s_addc_u32 s1, s1, 0
	v_cvt_pk_bf16_f32 v39, v206, v207
	global_store_short v13, v39, s[0:1]
	s_add_u32 s0, s0, 0x1000
	s_addc_u32 s1, s1, 0
	global_store_short_d16_hi v13, v39, s[0:1]
	s_waitcnt lgkmcnt(0)
	s_barrier
	s_mov_b32 s75, s92
	s_cbranch_vccz .LBB0_293
.LBB0_243:
	s_and_b32 s83, s33, 0x600
	s_waitcnt lgkmcnt(0)
	s_lshr_b32 s1, s75, 11
	s_mul_i32 s38, s1, 30
	s_and_b32 s0, s91, 0x100000fc
	s_lshl_b64 s[80:81], s[38:39], 13
	s_add_u32 s38, s87, s80
	s_addc_u32 s80, s88, s81
	s_cmpk_eq_i32 s0, 0xfc
	s_cselect_b64 s[0:1], -1, 0
	s_and_b64 s[92:93], s[0:1], exec
	s_cselect_b32 s81, s80, 0
	s_cselect_b32 s38, s38, 0
	s_lshl_b32 s80, s83, 2
	s_add_u32 s80, s38, s80
	s_addc_u32 s81, s81, 0
	v_lshl_add_u64 v[14:15], s[80:81], 0, v[50:51]
	s_andn2_b64 vcc, exec, s[4:5]
	s_cbranch_vccnz .LBB0_246
	s_and_b64 s[80:81], s[40:41], s[0:1]
	s_waitcnt vmcnt(0)
	v_lshlrev_b32_e32 v36, 16, v0
	v_and_b32_e32 v37, 0xffff0000, v0
	v_lshlrev_b32_e32 v38, 16, v1
	v_and_b32_e32 v39, 0xffff0000, v1
	v_lshlrev_b32_e32 v40, 16, v2
	v_and_b32_e32 v41, 0xffff0000, v2
	v_lshlrev_b32_e32 v42, 16, v3
	v_and_b32_e32 v43, 0xffff0000, v3
	s_andn2_b64 vcc, exec, s[80:81]
	ds_write_b128 v45, v[36:39]
	ds_write_b128 v45, v[40:43] offset:16
	s_cbranch_vccnz .LBB0_246
	v_lshl_add_u64 v[112:113], v[14:15], 0, s[42:43]
	global_store_dwordx4 v[112:113], v[36:39], off
	global_store_dwordx4 v[112:113], v[40:43], off offset:16
